# unit-boundary counted waits: first K-tile of a unit that follows an epilogue waits vmcnt(8+S) (S = epilogue VMEM ops) so result stores drain under the K-loop (Wo, up, down)
# speedup vs baseline: 1.0129x; 1.0129x over previous
; #define PG8_STAGE(bufoff, gbase, voff) do { _Pragma("unroll") for (int _i = 0; _i < 2; ++_i) \
;         __builtin_amdgcn_global_load_lds((const unsigned*)((const char*)(gbase) + (voff)[_i]), (PG8_LAS unsigned*)(lds + (bufoff) + ldsw + _i * 8192), 16, 0, 0); } while (0)
; #define PG8_WAIT_V(n) asm volatile("s_waitcnt vmcnt(" #n ")" ::: "memory")
; #define PG8_BAR __builtin_amdgcn_s_barrier()
; template <class Epi, class Sched, bool ALIGN_EPI = false, bool SP2 = false>
; __device__ __forceinline__ void gemm_phase(PG8_LAS unsigned char* lds, const Gemm g, const Sched& S, const Epi& E) {
;     ...
;     for (int i = 0; i < 2; ++i) { int R, C; stage_rc(tid * 16 + i * 8192, R, C); const int Rb = Epi::PERM ? ((R & ~31) + perm32(R & 31)) : R;
;         voffA[i] = (unsigned)(R * K + C) * 2u; voffB[i] = (unsigned)(Rb * K + C) * 2u; }
;     const size_t kstep = (size_t)(BK * 2);
;     const size_t hstep = (size_t)HALF * K * 2;
;     const size_t tstep = 2 * hstep;
;     const unsigned ldsw = (unsigned)wid * 1024u;
;     const int aoff = lds_byte(wr * 64 + fr, fq * 8), boff = lds_byte(wc * 32 + fr, fq * 8);
;     ...
;         PG8_WAIT_V(2); PG8_BAR;
;         PG8_STAGE(PG8_SB(1, 0), cB + kstep, voffB); PG8_STAGE(PG8_SA(1, 0), cA + kstep, voffA); PG8_STAGE(PG8_SB(1, 1), cB + hstep + kstep, voffB);
;         PG8_WAIT_V(6); PG8_BAR;
.LBB0_774:
	v_bfe_u32 v20, v11, 4, 2
	v_readlane_b32 s24, v254, 59
	v_and_b32_e32 v21, 15, v11
	v_lshlrev_b32_e32 v23, 4, v20
	v_lshlrev_b32_e32 v11, 2, v11
	v_mov_b32_e32 v195, v0
	v_readlane_b32 s25, v254, 60
	s_and_b32 s72, s15, 3
	v_lshl_or_b32 v23, v21, 6, v23
	s_lshl_b32 s13, s12, 13
	v_and_b32_e32 v11, 32, v11
	s_add_i32 m0, s28, 0x18000
	v_lshl_add_u64 v[2:3], v[2:3], 0, s[34:35]
	v_lshl_add_u64 v[12:13], s[24:25], 0, v[194:195]
	v_mov_b32_e32 v191, v0
	v_bitop3_b32 v24, v23, s13, v11 bitop3:0xde
	s_lshl_b32 s13, s72, 12
	s_waitcnt vmcnt(2)
	s_barrier
	global_load_lds_dwordx4 v[2:3], off
	v_lshl_add_u64 v[2:3], v[4:5], 0, s[34:35]
	s_add_i32 m0, s28, 0x1a000
	s_add_i32 s73, s28, 0x8000
	s_add_i32 s76, s28, 0xa000
	v_lshl_add_u64 v[18:19], s[24:25], 0, v[190:191]
	global_load_lds_dwordx4 v[2:3], off
	v_lshl_add_u64 v[2:3], v[12:13], 0, s[34:35]
	s_mov_b32 m0, s73
	s_add_u32 s16, s22, 0x40080
	global_load_lds_dwordx4 v[2:3], off
	v_lshl_add_u64 v[2:3], v[18:19], 0, s[34:35]
	s_mov_b32 m0, s76
	s_addc_u32 s17, s23, 0
	global_load_lds_dwordx4 v[2:3], off
	s_add_i32 m0, s28, 0x1c000
	v_lshl_add_u64 v[2:3], s[16:17], 0, v[192:193]
	global_load_lds_dwordx4 v[2:3], off
	v_lshl_add_u64 v[2:3], s[16:17], 0, v[14:15]
	s_add_i32 m0, s28, 0x1e000
	s_cmpk_lt_u32 s14, 0x100
	global_load_lds_dwordx4 v[2:3], off
	v_lshlrev_b32_e32 v2, 14, v9
	v_and_b32_e32 v2, 0xffff8000, v2
	v_lshl_add_u32 v2, v8, 11, v2
	v_and_b32_e32 v3, 1, v9
	v_lshl_or_b32 v2, v3, 6, v2
	v_lshl_or_b32 v222, s12, 6, v21
	s_cselect_b64 s[14:15], -1, 0
	s_lshl_b32 s12, s12, 9
	v_lshl_add_u32 v196, v10, 1, v2
	v_lshlrev_b32_e32 v2, 14, v1
	s_add_i32 s12, s12, 0
	v_and_b32_e32 v2, 0xffff8000, v2
	s_waitcnt vmcnt(6)
	s_add_i32 s12, s12, 0x20000
	v_lshl_add_u32 v2, v6, 11, v2
	v_and_b32_e32 v1, 1, v1
	v_lshlrev_b32_e32 v22, 3, v20
	v_bitop3_b32 v223, v23, s13, v11 bitop3:0xde
	v_lshl_add_u32 v225, v21, 3, s12
	v_lshl_or_b32 v1, v1, 6, v2
	v_readlane_b32 s12, v254, 53
	s_mov_b32 s26, 0
	v_cmp_eq_u32_e64 s[36:37], 0, v20
	v_lshl_or_b32 v224, s72, 5, v22
	v_mov_b32_e32 v197, v0
	v_lshl_add_u32 v198, v7, 1, v1
	v_mov_b32_e32 v199, v0
	v_add_u32_e32 v226, 0, v24
	v_readlane_b32 s20, v254, 30
	s_mov_b32 s27, s12
	s_mov_b64 s[16:17], s[24:25]
	s_barrier
	v_readlane_b32 s13, v254, 54
	s_mov_b32 s32, 1
	s_branch .LBB0_777

; #define PG8_BAR __builtin_amdgcn_s_barrier()
; template <class Epi, class Sched, bool ALIGN_EPI = false, bool SP2 = false>
; __device__ __forceinline__ void gemm_phase(PG8_LAS unsigned char* lds, const Gemm g, const Sched& S, const Epi& E) {
;     ...
;         if (!has_next) break;
; #pragma unroll
;         for (int a = 0; a < 2; ++a)
; #pragma unroll
;             for (int b = 0; b < 2; ++b)
; #pragma unroll
;                 for (int m = 0; m < 4; ++m)
; #pragma unroll
;                     for (int n = 0; n < 2; ++n) acc[a][b][m][n] = (f32x4){0.f, 0.f, 0.f, 0.f};
;         cur = nxt; cA = nA; cB = nB; ++ui;
;         if constexpr (ALIGN_EPI) { if (wr == 1) PG8_BAR; }
.LBB0_776:
	s_mov_b32 s32, -2
	s_andn2_b64 vcc, exec, s[16:17]
	s_mov_b32 s20, s40
	s_mov_b32 s27, s42
	s_mov_b64 s[22:23], s[82:83]
	s_mov_b64 s[16:17], s[50:51]
	s_mov_b32 s26, s77
	s_cbranch_vccz .LBB0_808

; #define PG8_STAGE(bufoff, gbase, voff) do { _Pragma("unroll") for (int _i = 0; _i < 2; ++_i) \
;         __builtin_amdgcn_global_load_lds((const unsigned*)((const char*)(gbase) + (voff)[_i]), (PG8_LAS unsigned*)(lds + (bufoff) + ldsw + _i * 8192), 16, 0, 0); } while (0)
; #define PG8_LDA(dst, b, h) do { _Pragma("unroll") for (int m = 0; m < 4; ++m) _Pragma("unroll") for (int k = 0; k < 2; ++k) dst[m][k] = *(const PG8_LAS bf16x8*)(lds + PG8_SA(b, h) + aoff + m * 2048 + k * 1024); } while (0)
; #define PG8_LDB(dst, b, h) do { _Pragma("unroll") for (int n = 0; n < 2; ++n) _Pragma("unroll") for (int k = 0; k < 2; ++k) dst[n][k] = *(const PG8_LAS bf16x8*)(lds + PG8_SB(b, h) + boff + n * 2048 + k * 1024); } while (0)
; #define PG8_MMA(ai, bj, At, Bt) do { __builtin_amdgcn_s_setprio(1); _Pragma("unroll") for (int m = 0; m < 4; ++m) _Pragma("unroll") for (int n = 0; n < 2; ++n) _Pragma("unroll") for (int k = 0; k < 2; ++k) \
;         acc[ai][bj][m][n] = __builtin_amdgcn_mfma_f32_16x16x32_f16(Bt[n][k], At[m][k], acc[ai][bj][m][n], 0, 0, 0); __builtin_amdgcn_s_setprio(0); } while (0)
; #define PG8_WAIT_V(n) asm volatile("s_waitcnt vmcnt(" #n ")" ::: "memory")
; #define PG8_WAIT_L(n) asm volatile("s_waitcnt lgkmcnt(" #n ")" ::: "memory")
; #define PG8_BAR __builtin_amdgcn_s_barrier()
; #define PG8_SCHED __builtin_amdgcn_sched_barrier(0)
; template <class Epi, class Sched, bool ALIGN_EPI = false, bool SP2 = false>
; __device__ __forceinline__ void gemm_phase(PG8_LAS unsigned char* lds, const Gemm g, const Sched& S, const Epi& E) {
;     ...
;             const char* a1 = cA + (size_t)(t + 1) * kstep;
;             const char* a2 = last ? nA : cA + (size_t)(t + 2) * kstep; const char* b2 = last ? nB : cB + (size_t)(t + 2) * kstep;
;             const char* a3 = a2 + kstep; const char* b3 = b2 + kstep;
;             if (last && has_next) S.a_ready(nxt);
;             if constexpr (SP2) {
;             PG8_LDB(B0, 0, 0); PG8_LDB(B1, 0, 1); PG8_SCHED; PG8_LDA(At, 0, 0); PG8_STAGE(PG8_SA(1, 1), a1 + hstep, voffA);
;             PG8_WAIT_V(8); PG8_WAIT_L(0); PG8_BAR; PG8_MMA(0, 0, At, B0); PG8_MMA(0, 1, At, B1); PG8_BAR; PG8_SCHED;
.LBB0_784:
	s_add_u32 s13, s16, 0xfffc0080
	s_addc_u32 s22, s17, -1
	s_add_i32 s92, 0, 0x10000
	s_cmp_eq_u32 s12, 12
	s_cselect_b32 s25, s29, s22
	s_cselect_b32 s24, s43, s13
	v_add_u32_e32 v1, s92, v223
	s_cselect_b32 s23, s41, vcc_hi
	s_cselect_b32 s22, s58, vcc_lo
	s_add_i32 s13, 0, 0x14000
	ds_read_b128 v[66:69], v1
	ds_read_b128 v[74:77], v1 offset:1024
	ds_read_b128 v[78:81], v1 offset:2048
	ds_read_b128 v[82:85], v1 offset:3072
	v_add_u32_e32 v1, s13, v223
	ds_read_b128 v[86:89], v1
	ds_read_b128 v[90:93], v1 offset:1024
	ds_read_b128 v[94:97], v1 offset:2048
	ds_read_b128 v[98:101], v1 offset:3072
	v_lshl_add_u64 v[208:209], s[16:17], 0, v[196:197]
	s_add_i32 m0, s28, 0xc000
	ds_read_b128 v[158:161], v226
	ds_read_b128 v[170:173], v226 offset:1024
	ds_read_b128 v[174:177], v226 offset:2048
	ds_read_b128 v[178:181], v226 offset:3072
	ds_read_b128 v[182:185], v226 offset:4096
	ds_read_b128 v[186:189], v226 offset:5120
	ds_read_b128 v[200:203], v226 offset:6144
	ds_read_b128 v[204:207], v226 offset:7168
	global_load_lds_dwordx4 v[208:209], off
	v_lshl_add_u64 v[208:209], s[16:17], 0, v[198:199]
	s_add_i32 m0, s28, 0xe000
	s_nop 0
	global_load_lds_dwordx4 v[208:209], off
	s_cmp_lg_u32 s12, s32
	s_cbranch_scc1 .Lfw8_784_0
	s_waitcnt vmcnt(40)
	s_branch .Lfwd_784_0

; #define PG8_STAGE(bufoff, gbase, voff) do { _Pragma("unroll") for (int _i = 0; _i < 2; ++_i) \
;         __builtin_amdgcn_global_load_lds((const unsigned*)((const char*)(gbase) + (voff)[_i]), (PG8_LAS unsigned*)(lds + (bufoff) + ldsw + _i * 8192), 16, 0, 0); } while (0)
; #define PG8_LDA(dst, b, h) do { _Pragma("unroll") for (int m = 0; m < 4; ++m) _Pragma("unroll") for (int k = 0; k < 2; ++k) dst[m][k] = *(const PG8_LAS bf16x8*)(lds + PG8_SA(b, h) + aoff + m * 2048 + k * 1024); } while (0)
; #define PG8_LDB(dst, b, h) do { _Pragma("unroll") for (int n = 0; n < 2; ++n) _Pragma("unroll") for (int k = 0; k < 2; ++k) dst[n][k] = *(const PG8_LAS bf16x8*)(lds + PG8_SB(b, h) + boff + n * 2048 + k * 1024); } while (0)
; #define PG8_MMA(ai, bj, At, Bt) do { __builtin_amdgcn_s_setprio(1); _Pragma("unroll") for (int m = 0; m < 4; ++m) _Pragma("unroll") for (int n = 0; n < 2; ++n) _Pragma("unroll") for (int k = 0; k < 2; ++k) \
;         acc[ai][bj][m][n] = __builtin_amdgcn_mfma_f32_16x16x32_f16(Bt[n][k], At[m][k], acc[ai][bj][m][n], 0, 0, 0); __builtin_amdgcn_s_setprio(0); } while (0)
; #define PG8_WAIT_V(n) asm volatile("s_waitcnt vmcnt(" #n ")" ::: "memory")
; #define PG8_WAIT_L(n) asm volatile("s_waitcnt lgkmcnt(" #n ")" ::: "memory")
; #define PG8_BAR __builtin_amdgcn_s_barrier()
; #define PG8_SCHED __builtin_amdgcn_sched_barrier(0)
; template <class Epi, class Sched, bool ALIGN_EPI = false, bool SP2 = false>
; __device__ __forceinline__ void gemm_phase(PG8_LAS unsigned char* lds, const Gemm g, const Sched& S, const Epi& E) {
;     ...
;             PG8_LDB(B0, 0, 0); PG8_LDB(B1, 0, 1); PG8_SCHED; PG8_LDA(At, 0, 0); PG8_STAGE(PG8_SA(1, 1), a1 + hstep, voffA);
;             PG8_WAIT_V(8); PG8_WAIT_L(0); PG8_BAR; PG8_MMA(0, 0, At, B0); PG8_MMA(0, 1, At, B1); PG8_BAR; PG8_SCHED;
;             PG8_LDA(At, 0, 1); PG8_STAGE(PG8_SB(0, 0), b2, voffB); PG8_STAGE(PG8_SB(0, 1), b2 + hstep, voffB); PG8_STAGE(PG8_SA(0, 0), a2, voffA);
;             PG8_WAIT_V(8); PG8_WAIT_L(0); PG8_BAR; PG8_MMA(1, 0, At, B0); PG8_MMA(1, 1, At, B1); PG8_BAR; PG8_SCHED;
.Lfwd_784_0:
	s_waitcnt lgkmcnt(0)
	s_barrier
	v_mfma_f32_16x16x32_f16 v[166:169], v[66:69], v[158:161], v[166:169]
	v_mfma_f32_16x16x32_f16 v[162:165], v[78:81], v[158:161], v[162:165]
	v_mfma_f32_16x16x32_f16 v[146:149], v[66:69], v[174:177], v[146:149]
	v_mfma_f32_16x16x32_f16 v[142:145], v[78:81], v[174:177], v[142:145]
	v_mfma_f32_16x16x32_f16 v[130:133], v[66:69], v[182:185], v[130:133]
	v_mfma_f32_16x16x32_f16 v[126:129], v[78:81], v[182:185], v[126:129]
	v_mfma_f32_16x16x32_f16 v[114:117], v[66:69], v[200:203], v[114:117]
	v_mfma_f32_16x16x32_f16 v[110:113], v[78:81], v[200:203], v[110:113]
	v_mfma_f32_16x16x32_f16 v[166:169], v[74:77], v[170:173], v[166:169]
	v_mfma_f32_16x16x32_f16 v[162:165], v[82:85], v[170:173], v[162:165]
	v_mfma_f32_16x16x32_f16 v[146:149], v[74:77], v[178:181], v[146:149]
	v_mfma_f32_16x16x32_f16 v[142:145], v[82:85], v[178:181], v[142:145]
	v_mfma_f32_16x16x32_f16 v[130:133], v[74:77], v[186:189], v[130:133]
	v_mfma_f32_16x16x32_f16 v[126:129], v[82:85], v[186:189], v[126:129]
	v_mfma_f32_16x16x32_f16 v[114:117], v[74:77], v[204:207], v[114:117]
	v_mfma_f32_16x16x32_f16 v[110:113], v[82:85], v[204:207], v[110:113]
	v_mfma_f32_16x16x32_f16 v[154:157], v[86:89], v[158:161], v[154:157]
	v_mfma_f32_16x16x32_f16 v[150:153], v[94:97], v[158:161], v[150:153]
	v_mfma_f32_16x16x32_f16 v[138:141], v[86:89], v[174:177], v[138:141]
	v_mfma_f32_16x16x32_f16 v[134:137], v[94:97], v[174:177], v[134:137]
	v_mfma_f32_16x16x32_f16 v[122:125], v[86:89], v[182:185], v[122:125]
	v_mfma_f32_16x16x32_f16 v[118:121], v[94:97], v[182:185], v[118:121]
	v_mfma_f32_16x16x32_f16 v[106:109], v[86:89], v[200:203], v[106:109]
	v_mfma_f32_16x16x32_f16 v[102:105], v[94:97], v[200:203], v[102:105]
	v_mfma_f32_16x16x32_f16 v[154:157], v[90:93], v[170:173], v[154:157]
	v_mfma_f32_16x16x32_f16 v[150:153], v[98:101], v[170:173], v[150:153]
	v_mfma_f32_16x16x32_f16 v[138:141], v[90:93], v[178:181], v[138:141]
	v_mfma_f32_16x16x32_f16 v[134:137], v[98:101], v[178:181], v[134:137]
	v_mfma_f32_16x16x32_f16 v[122:125], v[90:93], v[186:189], v[122:125]
	v_mfma_f32_16x16x32_f16 v[118:121], v[98:101], v[186:189], v[118:121]
	v_mfma_f32_16x16x32_f16 v[106:109], v[90:93], v[204:207], v[106:109]
	v_mfma_f32_16x16x32_f16 v[102:105], v[98:101], v[204:207], v[102:105]
	s_barrier
	s_add_i32 s92, s92, s11
	v_lshl_add_u64 v[208:209], s[22:23], 0, v[192:193]
	s_mov_b32 m0, s92
	ds_read_b128 v[158:161], v226 offset:16384
	ds_read_b128 v[170:173], v226 offset:17408
	ds_read_b128 v[174:177], v226 offset:18432
	ds_read_b128 v[178:181], v226 offset:19456
	ds_read_b128 v[182:185], v226 offset:20480
	ds_read_b128 v[186:189], v226 offset:21504
	ds_read_b128 v[200:203], v226 offset:22528
	ds_read_b128 v[204:207], v226 offset:23552
	global_load_lds_dwordx4 v[208:209], off
	s_add_i32 m0, s92, 0x2000
	s_add_u32 s92, s22, 0x40000
	v_lshl_add_u64 v[210:211], s[22:23], 0, v[14:15]
	s_addc_u32 s93, s23, 0
	s_add_i32 s13, s13, s11
	global_load_lds_dwordx4 v[210:211], off
	v_lshl_add_u64 v[212:213], s[92:93], 0, v[192:193]
	s_mov_b32 m0, s13
	v_lshl_add_u64 v[214:215], s[24:25], 0, v[190:191]
	global_load_lds_dwordx4 v[212:213], off
	v_lshl_add_u64 v[212:213], s[92:93], 0, v[14:15]
	s_add_i32 m0, s13, 0x2000
	s_nop 0
	global_load_lds_dwordx4 v[212:213], off
	v_lshl_add_u64 v[212:213], s[24:25], 0, v[194:195]
	s_mov_b32 m0, s28
	s_nop 0
	global_load_lds_dwordx4 v[212:213], off
	s_mov_b32 m0, s33
	s_nop 0
	global_load_lds_dwordx4 v[214:215], off
	s_cmp_lg_u32 s12, s32
	s_cbranch_scc1 .Lfw8_784_1
	s_waitcnt vmcnt(40)
	s_branch .Lfwd_784_1

; #define PG8_STAGE(bufoff, gbase, voff) do { _Pragma("unroll") for (int _i = 0; _i < 2; ++_i) \
;         __builtin_amdgcn_global_load_lds((const unsigned*)((const char*)(gbase) + (voff)[_i]), (PG8_LAS unsigned*)(lds + (bufoff) + ldsw + _i * 8192), 16, 0, 0); } while (0)
; #define PG8_LDA(dst, b, h) do { _Pragma("unroll") for (int m = 0; m < 4; ++m) _Pragma("unroll") for (int k = 0; k < 2; ++k) dst[m][k] = *(const PG8_LAS bf16x8*)(lds + PG8_SA(b, h) + aoff + m * 2048 + k * 1024); } while (0)
; #define PG8_LDB(dst, b, h) do { _Pragma("unroll") for (int n = 0; n < 2; ++n) _Pragma("unroll") for (int k = 0; k < 2; ++k) dst[n][k] = *(const PG8_LAS bf16x8*)(lds + PG8_SB(b, h) + boff + n * 2048 + k * 1024); } while (0)
; #define PG8_MMA(ai, bj, At, Bt) do { __builtin_amdgcn_s_setprio(1); _Pragma("unroll") for (int m = 0; m < 4; ++m) _Pragma("unroll") for (int n = 0; n < 2; ++n) _Pragma("unroll") for (int k = 0; k < 2; ++k) \
;         acc[ai][bj][m][n] = __builtin_amdgcn_mfma_f32_16x16x32_f16(Bt[n][k], At[m][k], acc[ai][bj][m][n], 0, 0, 0); __builtin_amdgcn_s_setprio(0); } while (0)
; #define PG8_WAIT_V(n) asm volatile("s_waitcnt vmcnt(" #n ")" ::: "memory")
; #define PG8_WAIT_L(n) asm volatile("s_waitcnt lgkmcnt(" #n ")" ::: "memory")
; #define PG8_BAR __builtin_amdgcn_s_barrier()
; #define PG8_SCHED __builtin_amdgcn_sched_barrier(0)
; template <class Epi, class Sched, bool ALIGN_EPI = false, bool SP2 = false>
; __device__ __forceinline__ void gemm_phase(PG8_LAS unsigned char* lds, const Gemm g, const Sched& S, const Epi& E) {
;     ...
;             PG8_WAIT_V(8); PG8_WAIT_L(0); PG8_BAR; PG8_MMA(1, 0, At, B0); PG8_MMA(1, 1, At, B1); PG8_BAR; PG8_SCHED;
;             PG8_LDB(B0, 1, 0); PG8_LDB(B1, 1, 1); PG8_SCHED; PG8_LDA(At, 1, 0); PG8_STAGE(PG8_SA(0, 1), a2 + hstep, voffA);
;             PG8_WAIT_V(8); PG8_WAIT_L(0); PG8_BAR; PG8_MMA(0, 0, At, B0); PG8_MMA(0, 1, At, B1); PG8_BAR; PG8_SCHED;
.Lfwd_784_1:
	s_waitcnt lgkmcnt(0)
	s_barrier
	v_mfma_f32_16x16x32_f16 v[70:73], v[66:69], v[158:161], v[70:73]
	v_mfma_f32_16x16x32_f16 v[62:65], v[78:81], v[158:161], v[62:65]
	v_mfma_f32_16x16x32_f16 v[50:53], v[66:69], v[174:177], v[50:53]
	v_mfma_f32_16x16x32_f16 v[46:49], v[78:81], v[174:177], v[46:49]
	v_mfma_f32_16x16x32_f16 v[34:37], v[66:69], v[182:185], v[34:37]
	v_mfma_f32_16x16x32_f16 v[30:33], v[78:81], v[182:185], v[30:33]
	v_mfma_f32_16x16x32_f16 v[18:21], v[66:69], v[200:203], v[18:21]
	v_mfma_f32_16x16x32_f16 v[10:13], v[78:81], v[200:203], v[10:13]
	v_mfma_f32_16x16x32_f16 v[70:73], v[74:77], v[170:173], v[70:73]
	v_mfma_f32_16x16x32_f16 v[62:65], v[82:85], v[170:173], v[62:65]
	v_mfma_f32_16x16x32_f16 v[50:53], v[74:77], v[178:181], v[50:53]
	v_mfma_f32_16x16x32_f16 v[46:49], v[82:85], v[178:181], v[46:49]
	v_mfma_f32_16x16x32_f16 v[34:37], v[74:77], v[186:189], v[34:37]
	v_mfma_f32_16x16x32_f16 v[30:33], v[82:85], v[186:189], v[30:33]
	v_mfma_f32_16x16x32_f16 v[18:21], v[74:77], v[204:207], v[18:21]
	v_mfma_f32_16x16x32_f16 v[10:13], v[82:85], v[204:207], v[10:13]
	v_mfma_f32_16x16x32_f16 v[58:61], v[86:89], v[158:161], v[58:61]
	v_mfma_f32_16x16x32_f16 v[54:57], v[94:97], v[158:161], v[54:57]
	v_mfma_f32_16x16x32_f16 v[42:45], v[86:89], v[174:177], v[42:45]
	v_mfma_f32_16x16x32_f16 v[38:41], v[94:97], v[174:177], v[38:41]
	v_mfma_f32_16x16x32_f16 v[26:29], v[86:89], v[182:185], v[26:29]
	v_mfma_f32_16x16x32_f16 v[22:25], v[94:97], v[182:185], v[22:25]
	v_mfma_f32_16x16x32_f16 v[6:9], v[86:89], v[200:203], v[6:9]
	v_mfma_f32_16x16x32_f16 v[2:5], v[94:97], v[200:203], v[2:5]
	v_mfma_f32_16x16x32_f16 v[58:61], v[90:93], v[170:173], v[58:61]
	v_mfma_f32_16x16x32_f16 v[54:57], v[98:101], v[170:173], v[54:57]
	v_mfma_f32_16x16x32_f16 v[42:45], v[90:93], v[178:181], v[42:45]
	v_mfma_f32_16x16x32_f16 v[38:41], v[98:101], v[178:181], v[38:41]
	v_mfma_f32_16x16x32_f16 v[26:29], v[90:93], v[186:189], v[26:29]
	v_mfma_f32_16x16x32_f16 v[22:25], v[98:101], v[186:189], v[22:25]
	v_mfma_f32_16x16x32_f16 v[6:9], v[90:93], v[204:207], v[6:9]
	v_mfma_f32_16x16x32_f16 v[2:5], v[98:101], v[204:207], v[2:5]
	s_barrier
	s_add_i32 s13, 0, 0x18000
	v_add_u32_e32 v1, s13, v223
	s_add_i32 s92, 0, 0x1c000
	ds_read_b128 v[66:69], v1
	ds_read_b128 v[74:77], v1 offset:1024
	ds_read_b128 v[78:81], v1 offset:2048
	ds_read_b128 v[82:85], v1 offset:3072
	v_add_u32_e32 v1, s92, v223
	ds_read_b128 v[86:89], v1
	ds_read_b128 v[90:93], v1 offset:1024
	ds_read_b128 v[94:97], v1 offset:2048
	ds_read_b128 v[98:101], v1 offset:3072
	s_add_u32 s24, s24, 0x40000
	s_addc_u32 s25, s25, 0
	s_mov_b32 m0, s49
	v_lshl_add_u64 v[218:219], s[24:25], 0, v[194:195]
	ds_read_b128 v[158:161], v226 offset:32768
	ds_read_b128 v[170:173], v226 offset:33792
	ds_read_b128 v[174:177], v226 offset:34816
	ds_read_b128 v[178:181], v226 offset:35840
	ds_read_b128 v[182:185], v226 offset:36864
	ds_read_b128 v[186:189], v226 offset:37888
	ds_read_b128 v[200:203], v226 offset:38912
	ds_read_b128 v[204:207], v226 offset:39936
	global_load_lds_dwordx4 v[218:219], off
	v_lshl_add_u64 v[218:219], s[24:25], 0, v[190:191]
	s_mov_b32 m0, s71
	s_nop 0
	global_load_lds_dwordx4 v[218:219], off
	s_waitcnt vmcnt(8)
	s_waitcnt lgkmcnt(0)
	s_barrier
	v_mfma_f32_16x16x32_f16 v[166:169], v[66:69], v[158:161], v[166:169]
	v_mfma_f32_16x16x32_f16 v[162:165], v[78:81], v[158:161], v[162:165]
	v_mfma_f32_16x16x32_f16 v[146:149], v[66:69], v[174:177], v[146:149]
	v_mfma_f32_16x16x32_f16 v[142:145], v[78:81], v[174:177], v[142:145]
	v_mfma_f32_16x16x32_f16 v[130:133], v[66:69], v[182:185], v[130:133]
	v_mfma_f32_16x16x32_f16 v[126:129], v[78:81], v[182:185], v[126:129]
	v_mfma_f32_16x16x32_f16 v[114:117], v[66:69], v[200:203], v[114:117]
	v_mfma_f32_16x16x32_f16 v[110:113], v[78:81], v[200:203], v[110:113]
	v_mfma_f32_16x16x32_f16 v[166:169], v[74:77], v[170:173], v[166:169]
	v_mfma_f32_16x16x32_f16 v[162:165], v[82:85], v[170:173], v[162:165]
	v_mfma_f32_16x16x32_f16 v[146:149], v[74:77], v[178:181], v[146:149]
	v_mfma_f32_16x16x32_f16 v[142:145], v[82:85], v[178:181], v[142:145]
	v_mfma_f32_16x16x32_f16 v[130:133], v[74:77], v[186:189], v[130:133]
	v_mfma_f32_16x16x32_f16 v[126:129], v[82:85], v[186:189], v[126:129]
	v_mfma_f32_16x16x32_f16 v[114:117], v[74:77], v[204:207], v[114:117]
	v_mfma_f32_16x16x32_f16 v[110:113], v[82:85], v[204:207], v[110:113]
	v_mfma_f32_16x16x32_f16 v[154:157], v[86:89], v[158:161], v[154:157]
	v_mfma_f32_16x16x32_f16 v[150:153], v[94:97], v[158:161], v[150:153]
	v_mfma_f32_16x16x32_f16 v[138:141], v[86:89], v[174:177], v[138:141]
	v_mfma_f32_16x16x32_f16 v[134:137], v[94:97], v[174:177], v[134:137]
	v_mfma_f32_16x16x32_f16 v[122:125], v[86:89], v[182:185], v[122:125]
	v_mfma_f32_16x16x32_f16 v[118:121], v[94:97], v[182:185], v[118:121]
	v_mfma_f32_16x16x32_f16 v[106:109], v[86:89], v[200:203], v[106:109]
	v_mfma_f32_16x16x32_f16 v[102:105], v[94:97], v[200:203], v[102:105]
	v_mfma_f32_16x16x32_f16 v[154:157], v[90:93], v[170:173], v[154:157]
	v_mfma_f32_16x16x32_f16 v[150:153], v[98:101], v[170:173], v[150:153]
	v_mfma_f32_16x16x32_f16 v[138:141], v[90:93], v[178:181], v[138:141]
	v_mfma_f32_16x16x32_f16 v[134:137], v[98:101], v[178:181], v[134:137]
	v_mfma_f32_16x16x32_f16 v[122:125], v[90:93], v[186:189], v[122:125]
	v_mfma_f32_16x16x32_f16 v[118:121], v[98:101], v[186:189], v[118:121]
	v_mfma_f32_16x16x32_f16 v[106:109], v[90:93], v[204:207], v[106:109]
	v_mfma_f32_16x16x32_f16 v[102:105], v[98:101], v[204:207], v[102:105]
	s_barrier
; #define PG8_STAGE(bufoff, gbase, voff) do { _Pragma("unroll") for (int _i = 0; _i < 2; ++_i) \
;         __builtin_amdgcn_global_load_lds((const unsigned*)((const char*)(gbase) + (voff)[_i]), (PG8_LAS unsigned*)(lds + (bufoff) + ldsw + _i * 8192), 16, 0, 0); } while (0)
; #define PG8_LDA(dst, b, h) do { _Pragma("unroll") for (int m = 0; m < 4; ++m) _Pragma("unroll") for (int k = 0; k < 2; ++k) dst[m][k] = *(const PG8_LAS bf16x8*)(lds + PG8_SA(b, h) + aoff + m * 2048 + k * 1024); } while (0)
; #define PG8_WAIT_V(n) asm volatile("s_waitcnt vmcnt(" #n ")" ::: "memory")
; #define PG8_WAIT_L(n) asm volatile("s_waitcnt lgkmcnt(" #n ")" ::: "memory")
; template <class Epi, class Sched, bool ALIGN_EPI = false, bool SP2 = false>
; __device__ __forceinline__ void gemm_phase(PG8_LAS unsigned char* lds, const Gemm g, const Sched& S, const Epi& E) {
;     ...
;         for (int t = 0; t < nt; t += 2) {
;             const bool last = (t == nt - 2);
;             const char* a1 = cA + (size_t)(t + 1) * kstep;
;             const char* a2 = last ? nA : cA + (size_t)(t + 2) * kstep; const char* b2 = last ? nB : cB + (size_t)(t + 2) * kstep;
;             const char* a3 = a2 + kstep; const char* b3 = b2 + kstep;
;             if (last && has_next) S.a_ready(nxt);
;             if constexpr (SP2) {
;             PG8_LDB(B0, 0, 0); PG8_LDB(B1, 0, 1); PG8_SCHED; PG8_LDA(At, 0, 0); PG8_STAGE(PG8_SA(1, 1), a1 + hstep, voffA);
;             PG8_WAIT_V(8); PG8_WAIT_L(0); PG8_BAR; PG8_MMA(0, 0, At, B0); PG8_MMA(0, 1, At, B1); PG8_BAR; PG8_SCHED;
;             PG8_LDA(At, 0, 1); PG8_STAGE(PG8_SB(0, 0), b2, voffB); PG8_STAGE(PG8_SB(0, 1), b2 + hstep, voffB); PG8_STAGE(PG8_SA(0, 0), a2, voffA);
;             PG8_WAIT_V(8); PG8_WAIT_L(0); PG8_BAR; PG8_MMA(1, 0, At, B0); PG8_MMA(1, 1, At, B1); PG8_BAR; PG8_SCHED;
;             PG8_LDB(B0, 1, 0); PG8_LDB(B1, 1, 1); PG8_SCHED; PG8_LDA(At, 1, 0); PG8_STAGE(PG8_SA(0, 1), a2 + hstep, voffA);
;             PG8_WAIT_V(8); PG8_WAIT_L(0); PG8_BAR; PG8_MMA(0, 0, At, B0); PG8_MMA(0, 1, At, B1); PG8_BAR; PG8_SCHED;
;             PG8_LDA(At, 1, 1); PG8_STAGE(PG8_SB(1, 0), b3, voffB); PG8_STAGE(PG8_SB(1, 1), b3 + hstep, voffB); PG8_STAGE(PG8_SA(1, 0), a3, voffA);
;             PG8_WAIT_V(8); PG8_WAIT_L(0); PG8_BAR; PG8_MMA(1, 0, At, B0); PG8_MMA(1, 1, At, B1); PG8_BAR; PG8_SCHED;
;     ...
;         if constexpr (ALIGN_EPI) { if (wr == 0) PG8_BAR; }
	s_add_i32 s13, s13, s11
	v_lshl_add_u64 v[208:209], v[208:209], 0, s[34:35]
	s_mov_b32 m0, s13
	ds_read_b128 v[158:161], v226 offset:49152
	ds_read_b128 v[170:173], v226 offset:50176
	ds_read_b128 v[174:177], v226 offset:51200
	ds_read_b128 v[178:181], v226 offset:52224
	ds_read_b128 v[182:185], v226 offset:53248
	ds_read_b128 v[186:189], v226 offset:54272
	ds_read_b128 v[200:203], v226 offset:55296
	ds_read_b128 v[204:207], v226 offset:56320
	global_load_lds_dwordx4 v[208:209], off
	s_add_i32 m0, s13, 0x2000
	s_add_u32 s22, s22, 0x40080
	v_lshl_add_u64 v[208:209], v[210:211], 0, s[34:35]
	s_addc_u32 s23, s23, 0
	s_add_i32 s13, s92, s11
	global_load_lds_dwordx4 v[208:209], off
	v_lshl_add_u64 v[208:209], s[22:23], 0, v[192:193]
	s_mov_b32 m0, s13
	s_nop 0
	global_load_lds_dwordx4 v[208:209], off
	v_lshl_add_u64 v[208:209], s[22:23], 0, v[14:15]
	s_add_i32 m0, s13, 0x2000
	s_nop 0
	global_load_lds_dwordx4 v[208:209], off
	v_lshl_add_u64 v[208:209], v[212:213], 0, s[34:35]
	s_mov_b32 m0, s73
	s_nop 0
	global_load_lds_dwordx4 v[208:209], off
	v_lshl_add_u64 v[208:209], v[214:215], 0, s[34:35]
	s_mov_b32 m0, s76
	s_nop 0
	global_load_lds_dwordx4 v[208:209], off
	s_waitcnt vmcnt(8)
	s_waitcnt lgkmcnt(0)
	s_barrier
	v_mfma_f32_16x16x32_f16 v[70:73], v[66:69], v[158:161], v[70:73]
	v_mfma_f32_16x16x32_f16 v[62:65], v[78:81], v[158:161], v[62:65]
	v_mfma_f32_16x16x32_f16 v[50:53], v[66:69], v[174:177], v[50:53]
	v_mfma_f32_16x16x32_f16 v[46:49], v[78:81], v[174:177], v[46:49]
	v_mfma_f32_16x16x32_f16 v[34:37], v[66:69], v[182:185], v[34:37]
	v_mfma_f32_16x16x32_f16 v[30:33], v[78:81], v[182:185], v[30:33]
	v_mfma_f32_16x16x32_f16 v[18:21], v[66:69], v[200:203], v[18:21]
	v_mfma_f32_16x16x32_f16 v[10:13], v[78:81], v[200:203], v[10:13]
	v_mfma_f32_16x16x32_f16 v[70:73], v[74:77], v[170:173], v[70:73]
	v_mfma_f32_16x16x32_f16 v[62:65], v[82:85], v[170:173], v[62:65]
	v_mfma_f32_16x16x32_f16 v[50:53], v[74:77], v[178:181], v[50:53]
	v_mfma_f32_16x16x32_f16 v[46:49], v[82:85], v[178:181], v[46:49]
	v_mfma_f32_16x16x32_f16 v[34:37], v[74:77], v[186:189], v[34:37]
	v_mfma_f32_16x16x32_f16 v[30:33], v[82:85], v[186:189], v[30:33]
	v_mfma_f32_16x16x32_f16 v[18:21], v[74:77], v[204:207], v[18:21]
	v_mfma_f32_16x16x32_f16 v[10:13], v[82:85], v[204:207], v[10:13]
	v_mfma_f32_16x16x32_f16 v[58:61], v[86:89], v[158:161], v[58:61]
	v_mfma_f32_16x16x32_f16 v[54:57], v[94:97], v[158:161], v[54:57]
	v_mfma_f32_16x16x32_f16 v[42:45], v[86:89], v[174:177], v[42:45]
	v_mfma_f32_16x16x32_f16 v[38:41], v[94:97], v[174:177], v[38:41]
	v_mfma_f32_16x16x32_f16 v[26:29], v[86:89], v[182:185], v[26:29]
	v_mfma_f32_16x16x32_f16 v[22:25], v[94:97], v[182:185], v[22:25]
	v_mfma_f32_16x16x32_f16 v[6:9], v[86:89], v[200:203], v[6:9]
	v_mfma_f32_16x16x32_f16 v[2:5], v[94:97], v[200:203], v[2:5]
	v_mfma_f32_16x16x32_f16 v[58:61], v[90:93], v[170:173], v[58:61]
	v_mfma_f32_16x16x32_f16 v[54:57], v[98:101], v[170:173], v[54:57]
	v_mfma_f32_16x16x32_f16 v[42:45], v[90:93], v[178:181], v[42:45]
	v_mfma_f32_16x16x32_f16 v[38:41], v[98:101], v[178:181], v[38:41]
	v_mfma_f32_16x16x32_f16 v[26:29], v[90:93], v[186:189], v[26:29]
	v_mfma_f32_16x16x32_f16 v[22:25], v[98:101], v[186:189], v[22:25]
	v_mfma_f32_16x16x32_f16 v[6:9], v[90:93], v[204:207], v[6:9]
	v_mfma_f32_16x16x32_f16 v[2:5], v[98:101], v[204:207], v[2:5]
	s_barrier
	s_add_i32 s12, s12, 2
	s_add_u32 s16, s16, 0x100
	s_addc_u32 s17, s17, 0
	s_add_u32 vcc_lo, vcc_lo, 0x100
	s_addc_u32 vcc_hi, vcc_hi, 0
	s_cmp_gt_u32 s12, 13
	s_cbranch_scc0 .LBB0_784
	s_and_b64 vcc, exec, s[14:15]
	s_cbranch_vccz .LBB0_787
	s_barrier

; #define PG8_STAGE(bufoff, gbase, voff) do { _Pragma("unroll") for (int _i = 0; _i < 2; ++_i) \
;         __builtin_amdgcn_global_load_lds((const unsigned*)((const char*)(gbase) + (voff)[_i]), (PG8_LAS unsigned*)(lds + (bufoff) + ldsw + _i * 8192), 16, 0, 0); } while (0)
; #define PG8_WAIT_V(n) asm volatile("s_waitcnt vmcnt(" #n ")" ::: "memory")
; #define PG8_BAR __builtin_amdgcn_s_barrier()
; template <class Epi, class Sched, bool ALIGN_EPI = false, bool SP2 = false>
; __device__ __forceinline__ void gemm_phase(PG8_LAS unsigned char* lds, const Gemm g, const Sched& S, const Epi& E) {
;     ...
;     for (int i = 0; i < 2; ++i) { int R, C; stage_rc(tid * 16 + i * 8192, R, C); const int Rb = Epi::PERM ? ((R & ~31) + perm32(R & 31)) : R;
;         voffA[i] = (unsigned)(R * K + C) * 2u; voffB[i] = (unsigned)(Rb * K + C) * 2u; }
;     const size_t kstep = (size_t)(BK * 2);
;     const size_t hstep = (size_t)HALF * K * 2;
;     const size_t tstep = 2 * hstep;
;     const unsigned ldsw = (unsigned)wid * 1024u;
;     const int aoff = lds_byte(wr * 64 + fr, fq * 8), boff = lds_byte(wc * 32 + fr, fq * 8);
;     ...
;         PG8_WAIT_V(2); PG8_BAR;
;         PG8_STAGE(PG8_SB(1, 0), cB + kstep, voffB); PG8_STAGE(PG8_SA(1, 0), cA + kstep, voffA); PG8_STAGE(PG8_SB(1, 1), cB + hstep + kstep, voffB);
;         PG8_WAIT_V(6); PG8_BAR;
.LBB0_814:
	v_mov_b32_e32 v161, v0
	v_bfe_u32 v21, v7, 4, 2
	v_lshl_add_u64 v[8:9], s[22:23], 0, v[160:161]
	v_mov_b32_e32 v15, v0
	v_readlane_b32 s24, v254, 59
	v_and_b32_e32 v20, 15, v7
	v_lshlrev_b32_e32 v23, 4, v21
	v_lshlrev_b32_e32 v7, 2, v7
	v_lshl_add_u64 v[10:11], s[22:23], 0, v[14:15]
	v_mov_b32_e32 v163, v0
	v_readlane_b32 s25, v254, 60
	s_and_b32 s72, s15, 3
	v_lshl_or_b32 v17, s14, 6, v20
	v_lshl_or_b32 v20, v20, 6, v23
	s_lshl_b32 s13, s14, 13
	v_and_b32_e32 v7, 32, v7
	s_add_i32 m0, s28, 0x18000
	v_lshl_add_u64 v[8:9], v[8:9], 0, s[34:35]
	v_lshl_add_u64 v[12:13], s[24:25], 0, v[162:163]
	v_mov_b32_e32 v159, v0
	v_bitop3_b32 v23, v20, s13, v7 bitop3:0xde
	s_lshl_b32 s13, s72, 12
	s_waitcnt vmcnt(2)
	s_barrier
	global_load_lds_dwordx4 v[8:9], off
	v_lshl_add_u64 v[8:9], v[10:11], 0, s[34:35]
	s_add_i32 m0, s28, 0x1a000
	s_add_i32 s73, s28, 0x8000
	s_add_i32 s76, s28, 0xa000
	v_lshl_add_u64 v[18:19], s[24:25], 0, v[158:159]
	global_load_lds_dwordx4 v[8:9], off
	v_lshl_add_u64 v[8:9], v[12:13], 0, s[34:35]
	s_mov_b32 m0, s73
	s_add_u32 s14, s22, 0x40080
	global_load_lds_dwordx4 v[8:9], off
	v_lshl_add_u64 v[8:9], v[18:19], 0, s[34:35]
	s_mov_b32 m0, s76
	s_addc_u32 s15, s23, 0
	global_load_lds_dwordx4 v[8:9], off
	s_add_i32 m0, s28, 0x1c000
	v_lshl_add_u64 v[8:9], s[14:15], 0, v[160:161]
	global_load_lds_dwordx4 v[8:9], off
	v_lshl_add_u64 v[8:9], s[14:15], 0, v[14:15]
	s_add_i32 m0, s28, 0x1e000
	v_bitop3_b32 v180, v20, s13, v7 bitop3:0xde
	global_load_lds_dwordx4 v[8:9], off
	v_lshlrev_b32_e32 v7, 14, v5
	v_and_b32_e32 v7, 0xffff8000, v7
	v_lshl_add_u32 v4, v4, 11, v7
	v_and_b32_e32 v5, 1, v5
	v_lshl_or_b32 v4, v5, 6, v4
	v_lshl_add_u32 v164, v6, 1, v4
	v_lshlrev_b32_e32 v4, 14, v1
	v_and_b32_e32 v4, 0xffff8000, v4
	s_waitcnt vmcnt(6)
	v_lshl_add_u32 v2, v2, 11, v4
	v_and_b32_e32 v1, 1, v1
	v_lshlrev_b32_e32 v22, 3, v21
	s_cmpk_lt_u32 s12, 0x100
	v_lshl_or_b32 v1, v1, 6, v2
	v_readlane_b32 s12, v254, 53
	v_lshl_or_b32 v181, s72, 5, v22
	s_cselect_b64 s[14:15], -1, 0
	s_mov_b32 s77, 0
	v_cmp_eq_u32_e64 s[36:37], 0, v21
	v_mov_b32_e32 v165, v0
	v_lshl_add_u32 v166, v3, 1, v1
	v_mov_b32_e32 v167, v0
	v_add_u32_e32 v182, 0, v23
	v_readlane_b32 s20, v254, 30
	s_mov_b32 s26, s12
	s_barrier
	v_readlane_b32 s13, v254, 54
	s_mov_b32 s32, 1
	s_branch .LBB0_817

; #define PG8_BAR __builtin_amdgcn_s_barrier()
; template <class Epi, class Sched, bool ALIGN_EPI = false, bool SP2 = false>
; __device__ __forceinline__ void gemm_phase(PG8_LAS unsigned char* lds, const Gemm g, const Sched& S, const Epi& E) {
;     ...
;         if (!has_next) break;
; #pragma unroll
;         for (int a = 0; a < 2; ++a)
; #pragma unroll
;             for (int b = 0; b < 2; ++b)
; #pragma unroll
;                 for (int m = 0; m < 4; ++m)
; #pragma unroll
;                     for (int n = 0; n < 2; ++n) acc[a][b][m][n] = (f32x4){0.f, 0.f, 0.f, 0.f};
;         cur = nxt; cA = nA; cB = nB; ++ui;
;         if constexpr (ALIGN_EPI) { if (wr == 1) PG8_BAR; }
.LBB0_816:
	s_mov_b32 s32, -2
	s_andn2_b64 vcc, exec, s[22:23]
	s_mov_b32 s20, s16
	s_mov_b32 s26, s40
	s_mov_b64 s[22:23], s[50:51]
	s_mov_b64 s[24:25], s[42:43]
	s_cbranch_vccz .LBB0_846

; #define PG8_STAGE(bufoff, gbase, voff) do { _Pragma("unroll") for (int _i = 0; _i < 2; ++_i) \
;         __builtin_amdgcn_global_load_lds((const unsigned*)((const char*)(gbase) + (voff)[_i]), (PG8_LAS unsigned*)(lds + (bufoff) + ldsw + _i * 8192), 16, 0, 0); } while (0)
; #define PG8_LDA(dst, b, h) do { _Pragma("unroll") for (int m = 0; m < 4; ++m) _Pragma("unroll") for (int k = 0; k < 2; ++k) dst[m][k] = *(const PG8_LAS bf16x8*)(lds + PG8_SA(b, h) + aoff + m * 2048 + k * 1024); } while (0)
; #define PG8_LDB(dst, b, h) do { _Pragma("unroll") for (int n = 0; n < 2; ++n) _Pragma("unroll") for (int k = 0; k < 2; ++k) dst[n][k] = *(const PG8_LAS bf16x8*)(lds + PG8_SB(b, h) + boff + n * 2048 + k * 1024); } while (0)
; #define PG8_MMA(ai, bj, At, Bt) do { __builtin_amdgcn_s_setprio(1); _Pragma("unroll") for (int m = 0; m < 4; ++m) _Pragma("unroll") for (int n = 0; n < 2; ++n) _Pragma("unroll") for (int k = 0; k < 2; ++k) \
;         acc[ai][bj][m][n] = __builtin_amdgcn_mfma_f32_16x16x32_f16(Bt[n][k], At[m][k], acc[ai][bj][m][n], 0, 0, 0); __builtin_amdgcn_s_setprio(0); } while (0)
; #define PG8_WAIT_V(n) asm volatile("s_waitcnt vmcnt(" #n ")" ::: "memory")
; #define PG8_WAIT_L(n) asm volatile("s_waitcnt lgkmcnt(" #n ")" ::: "memory")
; #define PG8_BAR __builtin_amdgcn_s_barrier()
; #define PG8_SCHED __builtin_amdgcn_sched_barrier(0)
; template <class Epi, class Sched, bool ALIGN_EPI = false, bool SP2 = false>
; __device__ __forceinline__ void gemm_phase(PG8_LAS unsigned char* lds, const Gemm g, const Sched& S, const Epi& E) {
;     ...
;             const char* a1 = cA + (size_t)(t + 1) * kstep;
;             const char* a2 = last ? nA : cA + (size_t)(t + 2) * kstep; const char* b2 = last ? nB : cB + (size_t)(t + 2) * kstep;
;             const char* a3 = a2 + kstep; const char* b3 = b2 + kstep;
;             if (last && has_next) S.a_ready(nxt);
;             if constexpr (SP2) {
;             PG8_LDB(B0, 0, 0); PG8_LDB(B1, 0, 1); PG8_SCHED; PG8_LDA(At, 0, 0); PG8_STAGE(PG8_SA(1, 1), a1 + hstep, voffA);
;             PG8_WAIT_V(8); PG8_WAIT_L(0); PG8_BAR; PG8_MMA(0, 0, At, B0); PG8_MMA(0, 1, At, B1); PG8_BAR; PG8_SCHED;
.LBB0_824:
	s_add_u32 s12, s82, 0xfffc0080
	s_addc_u32 s13, s83, -1
	s_add_i32 s92, 0, 0x10000
	s_cmp_eq_u32 vcc_hi, 12
	s_cselect_b32 s25, s27, s13
	s_cselect_b32 s24, s29, s12
	v_add_u32_e32 v1, s92, v180
	s_cselect_b32 s23, s17, vcc_lo
	s_cselect_b32 s22, s41, s58
	s_add_i32 s93, 0, 0x14000
	ds_read_b128 v[126:129], v1
	ds_read_b128 v[138:141], v1 offset:1024
	ds_read_b128 v[142:145], v1 offset:2048
	ds_read_b128 v[146:149], v1 offset:3072
	v_add_u32_e32 v1, s93, v180
	ds_read_b128 v[150:153], v1
	ds_read_b128 v[154:157], v1 offset:1024
	ds_read_b128 v[168:171], v1 offset:2048
	ds_read_b128 v[172:175], v1 offset:3072
	v_lshl_add_u64 v[212:213], s[82:83], 0, v[164:165]
	s_add_i32 m0, s28, 0xc000
	ds_read_b128 v[176:179], v182
	ds_read_b128 v[184:187], v182 offset:1024
	ds_read_b128 v[188:191], v182 offset:2048
	ds_read_b128 v[192:195], v182 offset:3072
	ds_read_b128 v[196:199], v182 offset:4096
	ds_read_b128 v[200:203], v182 offset:5120
	ds_read_b128 v[204:207], v182 offset:6144
	ds_read_b128 v[208:211], v182 offset:7168
	global_load_lds_dwordx4 v[212:213], off
	v_lshl_add_u64 v[212:213], s[82:83], 0, v[166:167]
	s_add_i32 m0, s28, 0xe000
	s_nop 0
	global_load_lds_dwordx4 v[212:213], off
	s_cmp_lg_u32 s12, s32
	s_cbranch_scc1 .Lfw8_824_0
	s_waitcnt vmcnt(40)
	s_branch .Lfwd_824_0

; #define PG8_STAGE(bufoff, gbase, voff) do { _Pragma("unroll") for (int _i = 0; _i < 2; ++_i) \
;         __builtin_amdgcn_global_load_lds((const unsigned*)((const char*)(gbase) + (voff)[_i]), (PG8_LAS unsigned*)(lds + (bufoff) + ldsw + _i * 8192), 16, 0, 0); } while (0)
; #define PG8_LDA(dst, b, h) do { _Pragma("unroll") for (int m = 0; m < 4; ++m) _Pragma("unroll") for (int k = 0; k < 2; ++k) dst[m][k] = *(const PG8_LAS bf16x8*)(lds + PG8_SA(b, h) + aoff + m * 2048 + k * 1024); } while (0)
; #define PG8_LDB(dst, b, h) do { _Pragma("unroll") for (int n = 0; n < 2; ++n) _Pragma("unroll") for (int k = 0; k < 2; ++k) dst[n][k] = *(const PG8_LAS bf16x8*)(lds + PG8_SB(b, h) + boff + n * 2048 + k * 1024); } while (0)
; #define PG8_MMA(ai, bj, At, Bt) do { __builtin_amdgcn_s_setprio(1); _Pragma("unroll") for (int m = 0; m < 4; ++m) _Pragma("unroll") for (int n = 0; n < 2; ++n) _Pragma("unroll") for (int k = 0; k < 2; ++k) \
;         acc[ai][bj][m][n] = __builtin_amdgcn_mfma_f32_16x16x32_f16(Bt[n][k], At[m][k], acc[ai][bj][m][n], 0, 0, 0); __builtin_amdgcn_s_setprio(0); } while (0)
; #define PG8_WAIT_V(n) asm volatile("s_waitcnt vmcnt(" #n ")" ::: "memory")
; #define PG8_WAIT_L(n) asm volatile("s_waitcnt lgkmcnt(" #n ")" ::: "memory")
; #define PG8_BAR __builtin_amdgcn_s_barrier()
; #define PG8_SCHED __builtin_amdgcn_sched_barrier(0)
; template <class Epi, class Sched, bool ALIGN_EPI = false, bool SP2 = false>
; __device__ __forceinline__ void gemm_phase(PG8_LAS unsigned char* lds, const Gemm g, const Sched& S, const Epi& E) {
;     ...
;             PG8_LDB(B0, 0, 0); PG8_LDB(B1, 0, 1); PG8_SCHED; PG8_LDA(At, 0, 0); PG8_STAGE(PG8_SA(1, 1), a1 + hstep, voffA);
;             PG8_WAIT_V(8); PG8_WAIT_L(0); PG8_BAR; PG8_MMA(0, 0, At, B0); PG8_MMA(0, 1, At, B1); PG8_BAR; PG8_SCHED;
;             PG8_LDA(At, 0, 1); PG8_STAGE(PG8_SB(0, 0), b2, voffB); PG8_STAGE(PG8_SB(0, 1), b2 + hstep, voffB); PG8_STAGE(PG8_SA(0, 0), a2, voffA);
;             PG8_WAIT_V(8); PG8_WAIT_L(0); PG8_BAR; PG8_MMA(1, 0, At, B0); PG8_MMA(1, 1, At, B1); PG8_BAR; PG8_SCHED;
.Lfwd_824_0:
	s_waitcnt lgkmcnt(0)
	s_barrier
	v_mfma_f32_16x16x32_f16 v[134:137], v[126:129], v[176:179], v[134:137]
	v_mfma_f32_16x16x32_f16 v[130:133], v[142:145], v[176:179], v[130:133]
	v_mfma_f32_16x16x32_f16 v[114:117], v[126:129], v[188:191], v[114:117]
	v_mfma_f32_16x16x32_f16 v[110:113], v[142:145], v[188:191], v[110:113]
	v_mfma_f32_16x16x32_f16 v[98:101], v[126:129], v[196:199], v[98:101]
	v_mfma_f32_16x16x32_f16 v[94:97], v[142:145], v[196:199], v[94:97]
	v_mfma_f32_16x16x32_f16 v[82:85], v[126:129], v[204:207], v[82:85]
	v_mfma_f32_16x16x32_f16 v[78:81], v[142:145], v[204:207], v[78:81]
	v_mfma_f32_16x16x32_f16 v[134:137], v[138:141], v[184:187], v[134:137]
	v_mfma_f32_16x16x32_f16 v[130:133], v[146:149], v[184:187], v[130:133]
	v_mfma_f32_16x16x32_f16 v[114:117], v[138:141], v[192:195], v[114:117]
	v_mfma_f32_16x16x32_f16 v[110:113], v[146:149], v[192:195], v[110:113]
	v_mfma_f32_16x16x32_f16 v[98:101], v[138:141], v[200:203], v[98:101]
	v_mfma_f32_16x16x32_f16 v[94:97], v[146:149], v[200:203], v[94:97]
	v_mfma_f32_16x16x32_f16 v[82:85], v[138:141], v[208:211], v[82:85]
	v_mfma_f32_16x16x32_f16 v[78:81], v[146:149], v[208:211], v[78:81]
	v_mfma_f32_16x16x32_f16 v[122:125], v[150:153], v[176:179], v[122:125]
	v_mfma_f32_16x16x32_f16 v[118:121], v[168:171], v[176:179], v[118:121]
	v_mfma_f32_16x16x32_f16 v[106:109], v[150:153], v[188:191], v[106:109]
	v_mfma_f32_16x16x32_f16 v[102:105], v[168:171], v[188:191], v[102:105]
	v_mfma_f32_16x16x32_f16 v[90:93], v[150:153], v[196:199], v[90:93]
	v_mfma_f32_16x16x32_f16 v[86:89], v[168:171], v[196:199], v[86:89]
	v_mfma_f32_16x16x32_f16 v[74:77], v[150:153], v[204:207], v[74:77]
	v_mfma_f32_16x16x32_f16 v[70:73], v[168:171], v[204:207], v[70:73]
	v_mfma_f32_16x16x32_f16 v[122:125], v[154:157], v[184:187], v[122:125]
	v_mfma_f32_16x16x32_f16 v[118:121], v[172:175], v[184:187], v[118:121]
	v_mfma_f32_16x16x32_f16 v[106:109], v[154:157], v[192:195], v[106:109]
	v_mfma_f32_16x16x32_f16 v[102:105], v[172:175], v[192:195], v[102:105]
	v_mfma_f32_16x16x32_f16 v[90:93], v[154:157], v[200:203], v[90:93]
	v_mfma_f32_16x16x32_f16 v[86:89], v[172:175], v[200:203], v[86:89]
	v_mfma_f32_16x16x32_f16 v[74:77], v[154:157], v[208:211], v[74:77]
	v_mfma_f32_16x16x32_f16 v[70:73], v[172:175], v[208:211], v[70:73]
	s_barrier
	s_add_i32 s12, s92, s11
	v_lshl_add_u64 v[212:213], s[22:23], 0, v[160:161]
	s_mov_b32 m0, s12
	ds_read_b128 v[176:179], v182 offset:16384
	ds_read_b128 v[184:187], v182 offset:17408
	ds_read_b128 v[188:191], v182 offset:18432
	ds_read_b128 v[192:195], v182 offset:19456
	ds_read_b128 v[196:199], v182 offset:20480
	ds_read_b128 v[200:203], v182 offset:21504
	ds_read_b128 v[204:207], v182 offset:22528
	ds_read_b128 v[208:211], v182 offset:23552
	global_load_lds_dwordx4 v[212:213], off
	s_add_i32 m0, s12, 0x2000
	s_add_u32 s12, s22, 0x40000
	v_lshl_add_u64 v[214:215], s[22:23], 0, v[14:15]
	s_addc_u32 s13, s23, 0
	s_add_i32 s92, s93, s11
	global_load_lds_dwordx4 v[214:215], off
	v_lshl_add_u64 v[218:219], s[12:13], 0, v[160:161]
	s_mov_b32 m0, s92
	v_lshl_add_u64 v[220:221], s[24:25], 0, v[158:159]
	global_load_lds_dwordx4 v[218:219], off
	v_lshl_add_u64 v[218:219], s[12:13], 0, v[14:15]
	s_add_i32 m0, s92, 0x2000
	s_nop 0
	global_load_lds_dwordx4 v[218:219], off
	v_lshl_add_u64 v[218:219], s[24:25], 0, v[162:163]
	s_mov_b32 m0, s28
	s_nop 0
	global_load_lds_dwordx4 v[218:219], off
	s_mov_b32 m0, s33
	s_nop 0
	global_load_lds_dwordx4 v[220:221], off
	s_cmp_lg_u32 s12, s32
	s_cbranch_scc1 .Lfw8_824_1
	s_waitcnt vmcnt(40)
	s_branch .Lfwd_824_1

; #define PG8_STAGE(bufoff, gbase, voff) do { _Pragma("unroll") for (int _i = 0; _i < 2; ++_i) \
;         __builtin_amdgcn_global_load_lds((const unsigned*)((const char*)(gbase) + (voff)[_i]), (PG8_LAS unsigned*)(lds + (bufoff) + ldsw + _i * 8192), 16, 0, 0); } while (0)
; #define PG8_LDA(dst, b, h) do { _Pragma("unroll") for (int m = 0; m < 4; ++m) _Pragma("unroll") for (int k = 0; k < 2; ++k) dst[m][k] = *(const PG8_LAS bf16x8*)(lds + PG8_SA(b, h) + aoff + m * 2048 + k * 1024); } while (0)
; #define PG8_LDB(dst, b, h) do { _Pragma("unroll") for (int n = 0; n < 2; ++n) _Pragma("unroll") for (int k = 0; k < 2; ++k) dst[n][k] = *(const PG8_LAS bf16x8*)(lds + PG8_SB(b, h) + boff + n * 2048 + k * 1024); } while (0)
; #define PG8_MMA(ai, bj, At, Bt) do { __builtin_amdgcn_s_setprio(1); _Pragma("unroll") for (int m = 0; m < 4; ++m) _Pragma("unroll") for (int n = 0; n < 2; ++n) _Pragma("unroll") for (int k = 0; k < 2; ++k) \
;         acc[ai][bj][m][n] = __builtin_amdgcn_mfma_f32_16x16x32_f16(Bt[n][k], At[m][k], acc[ai][bj][m][n], 0, 0, 0); __builtin_amdgcn_s_setprio(0); } while (0)
; #define PG8_WAIT_V(n) asm volatile("s_waitcnt vmcnt(" #n ")" ::: "memory")
; #define PG8_WAIT_L(n) asm volatile("s_waitcnt lgkmcnt(" #n ")" ::: "memory")
; #define PG8_BAR __builtin_amdgcn_s_barrier()
; #define PG8_SCHED __builtin_amdgcn_sched_barrier(0)
; template <class Epi, class Sched, bool ALIGN_EPI = false, bool SP2 = false>
; __device__ __forceinline__ void gemm_phase(PG8_LAS unsigned char* lds, const Gemm g, const Sched& S, const Epi& E) {
;     ...
;             PG8_WAIT_V(8); PG8_WAIT_L(0); PG8_BAR; PG8_MMA(1, 0, At, B0); PG8_MMA(1, 1, At, B1); PG8_BAR; PG8_SCHED;
;             PG8_LDB(B0, 1, 0); PG8_LDB(B1, 1, 1); PG8_SCHED; PG8_LDA(At, 1, 0); PG8_STAGE(PG8_SA(0, 1), a2 + hstep, voffA);
;             PG8_WAIT_V(8); PG8_WAIT_L(0); PG8_BAR; PG8_MMA(0, 0, At, B0); PG8_MMA(0, 1, At, B1); PG8_BAR; PG8_SCHED;
.Lfwd_824_1:
	s_waitcnt lgkmcnt(0)
	s_barrier
	v_mfma_f32_16x16x32_f16 v[66:69], v[126:129], v[176:179], v[66:69]
	v_mfma_f32_16x16x32_f16 v[62:65], v[142:145], v[176:179], v[62:65]
	v_mfma_f32_16x16x32_f16 v[50:53], v[126:129], v[188:191], v[50:53]
	v_mfma_f32_16x16x32_f16 v[46:49], v[142:145], v[188:191], v[46:49]
	v_mfma_f32_16x16x32_f16 v[34:37], v[126:129], v[196:199], v[34:37]
	v_mfma_f32_16x16x32_f16 v[30:33], v[142:145], v[196:199], v[30:33]
	v_mfma_f32_16x16x32_f16 v[18:21], v[126:129], v[204:207], v[18:21]
	v_mfma_f32_16x16x32_f16 v[10:13], v[142:145], v[204:207], v[10:13]
	v_mfma_f32_16x16x32_f16 v[66:69], v[138:141], v[184:187], v[66:69]
	v_mfma_f32_16x16x32_f16 v[62:65], v[146:149], v[184:187], v[62:65]
	v_mfma_f32_16x16x32_f16 v[50:53], v[138:141], v[192:195], v[50:53]
	v_mfma_f32_16x16x32_f16 v[46:49], v[146:149], v[192:195], v[46:49]
	v_mfma_f32_16x16x32_f16 v[34:37], v[138:141], v[200:203], v[34:37]
	v_mfma_f32_16x16x32_f16 v[30:33], v[146:149], v[200:203], v[30:33]
	v_mfma_f32_16x16x32_f16 v[18:21], v[138:141], v[208:211], v[18:21]
	v_mfma_f32_16x16x32_f16 v[10:13], v[146:149], v[208:211], v[10:13]
	v_mfma_f32_16x16x32_f16 v[58:61], v[150:153], v[176:179], v[58:61]
	v_mfma_f32_16x16x32_f16 v[54:57], v[168:171], v[176:179], v[54:57]
	v_mfma_f32_16x16x32_f16 v[42:45], v[150:153], v[188:191], v[42:45]
	v_mfma_f32_16x16x32_f16 v[38:41], v[168:171], v[188:191], v[38:41]
	v_mfma_f32_16x16x32_f16 v[26:29], v[150:153], v[196:199], v[26:29]
	v_mfma_f32_16x16x32_f16 v[22:25], v[168:171], v[196:199], v[22:25]
	v_mfma_f32_16x16x32_f16 v[6:9], v[150:153], v[204:207], v[6:9]
	v_mfma_f32_16x16x32_f16 v[2:5], v[168:171], v[204:207], v[2:5]
	v_mfma_f32_16x16x32_f16 v[58:61], v[154:157], v[184:187], v[58:61]
	v_mfma_f32_16x16x32_f16 v[54:57], v[172:175], v[184:187], v[54:57]
	v_mfma_f32_16x16x32_f16 v[42:45], v[154:157], v[192:195], v[42:45]
	v_mfma_f32_16x16x32_f16 v[38:41], v[172:175], v[192:195], v[38:41]
	v_mfma_f32_16x16x32_f16 v[26:29], v[154:157], v[200:203], v[26:29]
	v_mfma_f32_16x16x32_f16 v[22:25], v[172:175], v[200:203], v[22:25]
	v_mfma_f32_16x16x32_f16 v[6:9], v[154:157], v[208:211], v[6:9]
	v_mfma_f32_16x16x32_f16 v[2:5], v[172:175], v[208:211], v[2:5]
	s_barrier
	s_add_i32 s92, 0, 0x18000
	v_add_u32_e32 v1, s92, v180
	s_add_i32 s93, 0, 0x1c000
	ds_read_b128 v[126:129], v1
	ds_read_b128 v[138:141], v1 offset:1024
	ds_read_b128 v[142:145], v1 offset:2048
	ds_read_b128 v[146:149], v1 offset:3072
	v_add_u32_e32 v1, s93, v180
	ds_read_b128 v[150:153], v1
	ds_read_b128 v[154:157], v1 offset:1024
	ds_read_b128 v[168:171], v1 offset:2048
	ds_read_b128 v[172:175], v1 offset:3072
	s_add_u32 s12, s24, 0x40000
	s_addc_u32 s13, s25, 0
	s_mov_b32 m0, s49
	v_lshl_add_u64 v[222:223], s[12:13], 0, v[162:163]
	ds_read_b128 v[176:179], v182 offset:32768
	ds_read_b128 v[184:187], v182 offset:33792
	ds_read_b128 v[188:191], v182 offset:34816
	ds_read_b128 v[192:195], v182 offset:35840
	ds_read_b128 v[196:199], v182 offset:36864
	ds_read_b128 v[200:203], v182 offset:37888
	ds_read_b128 v[204:207], v182 offset:38912
	ds_read_b128 v[208:211], v182 offset:39936
	global_load_lds_dwordx4 v[222:223], off
	v_lshl_add_u64 v[222:223], s[12:13], 0, v[158:159]
	s_mov_b32 m0, s71
	s_nop 0
	global_load_lds_dwordx4 v[222:223], off
	s_waitcnt vmcnt(8)
	s_waitcnt lgkmcnt(0)
	s_barrier
	v_mfma_f32_16x16x32_f16 v[134:137], v[126:129], v[176:179], v[134:137]
	v_mfma_f32_16x16x32_f16 v[130:133], v[142:145], v[176:179], v[130:133]
	v_mfma_f32_16x16x32_f16 v[114:117], v[126:129], v[188:191], v[114:117]
	v_mfma_f32_16x16x32_f16 v[110:113], v[142:145], v[188:191], v[110:113]
	v_mfma_f32_16x16x32_f16 v[98:101], v[126:129], v[196:199], v[98:101]
	v_mfma_f32_16x16x32_f16 v[94:97], v[142:145], v[196:199], v[94:97]
	v_mfma_f32_16x16x32_f16 v[82:85], v[126:129], v[204:207], v[82:85]
	v_mfma_f32_16x16x32_f16 v[78:81], v[142:145], v[204:207], v[78:81]
	v_mfma_f32_16x16x32_f16 v[134:137], v[138:141], v[184:187], v[134:137]
	v_mfma_f32_16x16x32_f16 v[130:133], v[146:149], v[184:187], v[130:133]
	v_mfma_f32_16x16x32_f16 v[114:117], v[138:141], v[192:195], v[114:117]
	v_mfma_f32_16x16x32_f16 v[110:113], v[146:149], v[192:195], v[110:113]
	v_mfma_f32_16x16x32_f16 v[98:101], v[138:141], v[200:203], v[98:101]
	v_mfma_f32_16x16x32_f16 v[94:97], v[146:149], v[200:203], v[94:97]
	v_mfma_f32_16x16x32_f16 v[82:85], v[138:141], v[208:211], v[82:85]
	v_mfma_f32_16x16x32_f16 v[78:81], v[146:149], v[208:211], v[78:81]
	v_mfma_f32_16x16x32_f16 v[122:125], v[150:153], v[176:179], v[122:125]
	v_mfma_f32_16x16x32_f16 v[118:121], v[168:171], v[176:179], v[118:121]
	v_mfma_f32_16x16x32_f16 v[106:109], v[150:153], v[188:191], v[106:109]
	v_mfma_f32_16x16x32_f16 v[102:105], v[168:171], v[188:191], v[102:105]
	v_mfma_f32_16x16x32_f16 v[90:93], v[150:153], v[196:199], v[90:93]
	v_mfma_f32_16x16x32_f16 v[86:89], v[168:171], v[196:199], v[86:89]
	v_mfma_f32_16x16x32_f16 v[74:77], v[150:153], v[204:207], v[74:77]
	v_mfma_f32_16x16x32_f16 v[70:73], v[168:171], v[204:207], v[70:73]
	v_mfma_f32_16x16x32_f16 v[122:125], v[154:157], v[184:187], v[122:125]
	v_mfma_f32_16x16x32_f16 v[118:121], v[172:175], v[184:187], v[118:121]
	v_mfma_f32_16x16x32_f16 v[106:109], v[154:157], v[192:195], v[106:109]
	v_mfma_f32_16x16x32_f16 v[102:105], v[172:175], v[192:195], v[102:105]
	v_mfma_f32_16x16x32_f16 v[90:93], v[154:157], v[200:203], v[90:93]
	v_mfma_f32_16x16x32_f16 v[86:89], v[172:175], v[200:203], v[86:89]
	v_mfma_f32_16x16x32_f16 v[74:77], v[154:157], v[208:211], v[74:77]
	v_mfma_f32_16x16x32_f16 v[70:73], v[172:175], v[208:211], v[70:73]
	s_barrier
; #define PG8_STAGE(bufoff, gbase, voff) do { _Pragma("unroll") for (int _i = 0; _i < 2; ++_i) \
;         __builtin_amdgcn_global_load_lds((const unsigned*)((const char*)(gbase) + (voff)[_i]), (PG8_LAS unsigned*)(lds + (bufoff) + ldsw + _i * 8192), 16, 0, 0); } while (0)
; #define PG8_LDA(dst, b, h) do { _Pragma("unroll") for (int m = 0; m < 4; ++m) _Pragma("unroll") for (int k = 0; k < 2; ++k) dst[m][k] = *(const PG8_LAS bf16x8*)(lds + PG8_SA(b, h) + aoff + m * 2048 + k * 1024); } while (0)
; #define PG8_MMA(ai, bj, At, Bt) do { __builtin_amdgcn_s_setprio(1); _Pragma("unroll") for (int m = 0; m < 4; ++m) _Pragma("unroll") for (int n = 0; n < 2; ++n) _Pragma("unroll") for (int k = 0; k < 2; ++k) \
;         acc[ai][bj][m][n] = __builtin_amdgcn_mfma_f32_16x16x32_f16(Bt[n][k], At[m][k], acc[ai][bj][m][n], 0, 0, 0); __builtin_amdgcn_s_setprio(0); } while (0)
; #define PG8_WAIT_V(n) asm volatile("s_waitcnt vmcnt(" #n ")" ::: "memory")
; #define PG8_WAIT_L(n) asm volatile("s_waitcnt lgkmcnt(" #n ")" ::: "memory")
; #define PG8_BAR __builtin_amdgcn_s_barrier()
; #define PG8_SCHED __builtin_amdgcn_sched_barrier(0)
; template <class Epi, class Sched, bool ALIGN_EPI = false, bool SP2 = false>
; __device__ __forceinline__ void gemm_phase(PG8_LAS unsigned char* lds, const Gemm g, const Sched& S, const Epi& E) {
;     ...
;             PG8_LDA(At, 1, 1); PG8_STAGE(PG8_SB(1, 0), b3, voffB); PG8_STAGE(PG8_SB(1, 1), b3 + hstep, voffB); PG8_STAGE(PG8_SA(1, 0), a3, voffA);
;             PG8_WAIT_V(8); PG8_WAIT_L(0); PG8_BAR; PG8_MMA(1, 0, At, B0); PG8_MMA(1, 1, At, B1); PG8_BAR; PG8_SCHED;
	s_add_i32 s12, s92, s11
	v_lshl_add_u64 v[212:213], v[212:213], 0, s[34:35]
	s_mov_b32 m0, s12
	ds_read_b128 v[176:179], v182 offset:49152
	ds_read_b128 v[184:187], v182 offset:50176
	ds_read_b128 v[188:191], v182 offset:51200
	ds_read_b128 v[192:195], v182 offset:52224
	ds_read_b128 v[196:199], v182 offset:53248
	ds_read_b128 v[200:203], v182 offset:54272
	ds_read_b128 v[204:207], v182 offset:55296
	ds_read_b128 v[208:211], v182 offset:56320
	global_load_lds_dwordx4 v[212:213], off
	s_add_i32 m0, s12, 0x2000
	s_add_u32 s12, s22, 0x40080
	v_lshl_add_u64 v[212:213], v[214:215], 0, s[34:35]
	s_addc_u32 s13, s23, 0
	s_add_i32 s22, s93, s11
	global_load_lds_dwordx4 v[212:213], off
	v_lshl_add_u64 v[212:213], s[12:13], 0, v[160:161]
	s_mov_b32 m0, s22
	s_nop 0
	global_load_lds_dwordx4 v[212:213], off
	v_lshl_add_u64 v[212:213], s[12:13], 0, v[14:15]
	s_add_i32 m0, s22, 0x2000
	s_nop 0
	global_load_lds_dwordx4 v[212:213], off
	v_lshl_add_u64 v[212:213], v[218:219], 0, s[34:35]
	s_mov_b32 m0, s73
	s_nop 0
	global_load_lds_dwordx4 v[212:213], off
	v_lshl_add_u64 v[212:213], v[220:221], 0, s[34:35]
	s_mov_b32 m0, s76
	s_nop 0
	global_load_lds_dwordx4 v[212:213], off
	s_waitcnt vmcnt(8)
	s_waitcnt lgkmcnt(0)
	s_barrier
	v_mfma_f32_16x16x32_f16 v[66:69], v[126:129], v[176:179], v[66:69]
	v_mfma_f32_16x16x32_f16 v[62:65], v[142:145], v[176:179], v[62:65]
	v_mfma_f32_16x16x32_f16 v[50:53], v[126:129], v[188:191], v[50:53]
	v_mfma_f32_16x16x32_f16 v[46:49], v[142:145], v[188:191], v[46:49]
	v_mfma_f32_16x16x32_f16 v[34:37], v[126:129], v[196:199], v[34:37]
	v_mfma_f32_16x16x32_f16 v[30:33], v[142:145], v[196:199], v[30:33]
	v_mfma_f32_16x16x32_f16 v[18:21], v[126:129], v[204:207], v[18:21]
	v_mfma_f32_16x16x32_f16 v[10:13], v[142:145], v[204:207], v[10:13]
	v_mfma_f32_16x16x32_f16 v[66:69], v[138:141], v[184:187], v[66:69]
	v_mfma_f32_16x16x32_f16 v[62:65], v[146:149], v[184:187], v[62:65]
	v_mfma_f32_16x16x32_f16 v[50:53], v[138:141], v[192:195], v[50:53]
	v_mfma_f32_16x16x32_f16 v[46:49], v[146:149], v[192:195], v[46:49]
	v_mfma_f32_16x16x32_f16 v[34:37], v[138:141], v[200:203], v[34:37]
	v_mfma_f32_16x16x32_f16 v[30:33], v[146:149], v[200:203], v[30:33]
	v_mfma_f32_16x16x32_f16 v[18:21], v[138:141], v[208:211], v[18:21]
	v_mfma_f32_16x16x32_f16 v[10:13], v[146:149], v[208:211], v[10:13]
	v_mfma_f32_16x16x32_f16 v[58:61], v[150:153], v[176:179], v[58:61]
	v_mfma_f32_16x16x32_f16 v[54:57], v[168:171], v[176:179], v[54:57]
	v_mfma_f32_16x16x32_f16 v[42:45], v[150:153], v[188:191], v[42:45]
	v_mfma_f32_16x16x32_f16 v[38:41], v[168:171], v[188:191], v[38:41]
	v_mfma_f32_16x16x32_f16 v[26:29], v[150:153], v[196:199], v[26:29]
	v_mfma_f32_16x16x32_f16 v[22:25], v[168:171], v[196:199], v[22:25]
	v_mfma_f32_16x16x32_f16 v[6:9], v[150:153], v[204:207], v[6:9]
	v_mfma_f32_16x16x32_f16 v[2:5], v[168:171], v[204:207], v[2:5]
	v_mfma_f32_16x16x32_f16 v[58:61], v[154:157], v[184:187], v[58:61]
	v_mfma_f32_16x16x32_f16 v[54:57], v[172:175], v[184:187], v[54:57]
	v_mfma_f32_16x16x32_f16 v[42:45], v[154:157], v[192:195], v[42:45]
	v_mfma_f32_16x16x32_f16 v[38:41], v[172:175], v[192:195], v[38:41]
	v_mfma_f32_16x16x32_f16 v[26:29], v[154:157], v[200:203], v[26:29]
	v_mfma_f32_16x16x32_f16 v[22:25], v[172:175], v[200:203], v[22:25]
	v_mfma_f32_16x16x32_f16 v[6:9], v[154:157], v[208:211], v[6:9]
	v_mfma_f32_16x16x32_f16 v[2:5], v[172:175], v[208:211], v[2:5]
	s_barrier
	s_add_i32 vcc_hi, vcc_hi, 2
	s_add_u32 s82, s82, 0x100
	s_addc_u32 s83, s83, 0
	s_add_u32 s58, s58, 0x100
	s_addc_u32 vcc_lo, vcc_lo, 0
	s_cmp_gt_u32 vcc_hi, 13
	s_cbranch_scc0 .LBB0_824
	s_and_b64 vcc, exec, s[14:15]
	s_cbranch_vccz .LBB0_827
	s_barrier

; #define PG8_STAGE(bufoff, gbase, voff) do { _Pragma("unroll") for (int _i = 0; _i < 2; ++_i) \
;         __builtin_amdgcn_global_load_lds((const unsigned*)((const char*)(gbase) + (voff)[_i]), (PG8_LAS unsigned*)(lds + (bufoff) + ldsw + _i * 8192), 16, 0, 0); } while (0)
; #define PG8_WAIT_V(n) asm volatile("s_waitcnt vmcnt(" #n ")" ::: "memory")
; #define PG8_BAR __builtin_amdgcn_s_barrier()
; template <class Epi, class Sched, bool ALIGN_EPI = false, bool SP2 = false>
; __device__ __forceinline__ void gemm_phase(PG8_LAS unsigned char* lds, const Gemm g, const Sched& S, const Epi& E) {
;     ...
;     for (int i = 0; i < 2; ++i) { int R, C; stage_rc(tid * 16 + i * 8192, R, C); const int Rb = Epi::PERM ? ((R & ~31) + perm32(R & 31)) : R;
;         voffA[i] = (unsigned)(R * K + C) * 2u; voffB[i] = (unsigned)(Rb * K + C) * 2u; }
;     const size_t kstep = (size_t)(BK * 2);
;     const size_t hstep = (size_t)HALF * K * 2;
;     const size_t tstep = 2 * hstep;
;     const unsigned ldsw = (unsigned)wid * 1024u;
;     const int aoff = lds_byte(wr * 64 + fr, fq * 8), boff = lds_byte(wc * 32 + fr, fq * 8);
;     ...
;     if constexpr (SP2) {
;         PG8_STAGE(PG8_SB(0, 0), cB, voffB); PG8_STAGE(PG8_SB(0, 1), cB + hstep, voffB); PG8_STAGE(PG8_SA(0, 0), cA, voffA); PG8_STAGE(PG8_SA(0, 1), cA + hstep, voffA);
;         if (wr == 1) PG8_BAR;
;         PG8_WAIT_V(2); PG8_BAR;
;         PG8_STAGE(PG8_SB(1, 0), cB + kstep, voffB); PG8_STAGE(PG8_SA(1, 0), cA + kstep, voffA); PG8_STAGE(PG8_SB(1, 1), cB + hstep + kstep, voffB);
;         PG8_WAIT_V(6); PG8_BAR;
.LBB0_976:
	v_lshrrev_b32_e32 v17, 1, v12
	v_and_b32_e32 v22, 24, v17
	v_and_b32_e32 v13, 15, v12
	v_lshlrev_b32_e32 v17, 1, v22
	v_lshlrev_b32_e32 v12, 2, v12
	v_lshl_or_b32 v17, v13, 6, v17
	s_lshl_b32 s13, s12, 13
	v_and_b32_e32 v12, 32, v12
	v_readlane_b32 s24, v254, 33
	v_bitop3_b32 v23, v17, s13, v12 bitop3:0xde
	s_lshl_b32 s13, s15, 5
	v_mov_b32_e32 v171, v0
	v_readlane_b32 s25, v254, 34
	s_and_b32 s13, s13, 0x60
	s_add_i32 m0, s20, 0x18000
	v_lshl_add_u64 v[2:3], v[2:3], 0, s[34:35]
	v_lshl_add_u64 v[18:19], s[24:25], 0, v[170:171]
	v_mov_b32_e32 v167, v0
	s_lshl_b32 s15, s13, 7
	s_waitcnt vmcnt(2)
	s_barrier
	global_load_lds_dwordx4 v[2:3], off
	v_lshl_add_u64 v[2:3], v[4:5], 0, s[34:35]
	s_add_i32 m0, s20, 0x1a000
	s_add_i32 s29, s20, 0x8000
	s_add_i32 s33, s20, 0xa000
	v_lshl_add_u64 v[20:21], s[24:25], 0, v[166:167]
	global_load_lds_dwordx4 v[2:3], off
	v_lshl_add_u64 v[2:3], v[18:19], 0, s[34:35]
	s_mov_b32 m0, s29
	s_add_u32 s16, s22, 0x40080
	global_load_lds_dwordx4 v[2:3], off
	v_lshl_add_u64 v[2:3], v[20:21], 0, s[34:35]
	s_mov_b32 m0, s33
	s_addc_u32 s17, s23, 0
	global_load_lds_dwordx4 v[2:3], off
	s_add_i32 m0, s20, 0x1c000
	v_lshl_add_u64 v[2:3], s[16:17], 0, v[168:169]
	global_load_lds_dwordx4 v[2:3], off
	v_lshl_add_u64 v[2:3], s[16:17], 0, v[14:15]
	s_add_i32 m0, s20, 0x1e000
	s_cmpk_lt_u32 s14, 0x100
	global_load_lds_dwordx4 v[2:3], off
	v_lshlrev_b32_e32 v2, 14, v10
	v_and_b32_e32 v2, 0xffff8000, v2
	v_lshl_add_u32 v2, v9, 11, v2
	v_and_b32_e32 v3, 1, v10
	v_lshl_or_b32 v2, v3, 6, v2
	v_lshl_or_b32 v1, s12, 6, v13
	v_bitop3_b32 v17, v17, s15, v12 bitop3:0xde
	s_cselect_b64 s[14:15], -1, 0
	s_lshl_b32 s12, s12, 9
	v_lshl_add_u32 v172, v11, 1, v2
	v_lshlrev_b32_e32 v2, 14, v6
	s_add_i32 s12, s12, 0
	v_and_b32_e32 v2, 0xffff8000, v2
	s_waitcnt vmcnt(6)
	s_add_i32 s12, s12, 0x20000
	v_lshl_add_u32 v2, v7, 11, v2
	v_and_b32_e32 v3, 1, v6
	v_or_b32_e32 v182, s13, v22
	v_lshl_add_u32 v183, v13, 3, s12
	v_lshl_or_b32 v2, v3, 6, v2
	v_readlane_b32 s12, v254, 31
	v_mov_b32_e32 v173, v0
	v_lshl_add_u32 v174, v8, 1, v2
	v_mov_b32_e32 v175, v0
	s_mov_b32 s72, 0
	v_add_u32_e32 v184, 0, v23
	v_readlane_b32 s58, v254, 26
	s_mov_b32 s71, s12
	s_barrier
	v_readlane_b32 s13, v254, 32
	s_mov_b32 s32, 1
	s_branch .LBB0_979

; #define PG8_BAR __builtin_amdgcn_s_barrier()
; template <class Epi, class Sched, bool ALIGN_EPI = false, bool SP2 = false>
; __device__ __forceinline__ void gemm_phase(PG8_LAS unsigned char* lds, const Gemm g, const Sched& S, const Epi& E) {
;     ...
;         if (!has_next) break;
; #pragma unroll
;         for (int a = 0; a < 2; ++a)
; #pragma unroll
;             for (int b = 0; b < 2; ++b)
; #pragma unroll
;                 for (int m = 0; m < 4; ++m)
; #pragma unroll
;                     for (int n = 0; n < 2; ++n) acc[a][b][m][n] = (f32x4){0.f, 0.f, 0.f, 0.f};
;         cur = nxt; cA = nA; cB = nB; ++ui;
;         if constexpr (ALIGN_EPI) { if (wr == 1) PG8_BAR; }
.LBB0_978:
	s_mov_b32 s32, -2
	s_andn2_b64 vcc, exec, s[22:23]
	s_mov_b32 s58, s16
	s_mov_b32 s71, s38
	s_mov_b64 s[22:23], s[42:43]
	s_mov_b64 s[24:25], s[40:41]
	s_mov_b32 s72, s49
	s_cbranch_vccz .LBB0_994

; #define PG8_STAGE(bufoff, gbase, voff) do { _Pragma("unroll") for (int _i = 0; _i < 2; ++_i) \
;         __builtin_amdgcn_global_load_lds((const unsigned*)((const char*)(gbase) + (voff)[_i]), (PG8_LAS unsigned*)(lds + (bufoff) + ldsw + _i * 8192), 16, 0, 0); } while (0)
; #define PG8_LDA(dst, b, h) do { _Pragma("unroll") for (int m = 0; m < 4; ++m) _Pragma("unroll") for (int k = 0; k < 2; ++k) dst[m][k] = *(const PG8_LAS bf16x8*)(lds + PG8_SA(b, h) + aoff + m * 2048 + k * 1024); } while (0)
; #define PG8_LDB(dst, b, h) do { _Pragma("unroll") for (int n = 0; n < 2; ++n) _Pragma("unroll") for (int k = 0; k < 2; ++k) dst[n][k] = *(const PG8_LAS bf16x8*)(lds + PG8_SB(b, h) + boff + n * 2048 + k * 1024); } while (0)
; #define PG8_SCHED __builtin_amdgcn_sched_barrier(0)
; template <class Epi, class Sched, bool ALIGN_EPI = false, bool SP2 = false>
; __device__ __forceinline__ void gemm_phase(PG8_LAS unsigned char* lds, const Gemm g, const Sched& S, const Epi& E) {
;     ...
;             const bool last = (t == nt - 2);
;             const char* a1 = cA + (size_t)(t + 1) * kstep;
;             const char* a2 = last ? nA : cA + (size_t)(t + 2) * kstep; const char* b2 = last ? nB : cB + (size_t)(t + 2) * kstep;
;             const char* a3 = a2 + kstep; const char* b3 = b2 + kstep;
;             if (last && has_next) S.a_ready(nxt);
;             if constexpr (SP2) {
;             PG8_LDB(B0, 0, 0); PG8_LDB(B1, 0, 1); PG8_SCHED; PG8_LDA(At, 0, 0); PG8_STAGE(PG8_SA(1, 1), a1 + hstep, voffA);
.LBB0_986:
	s_add_u32 s13, s50, 0xfffc0080
	s_addc_u32 s22, s51, -1
	s_add_i32 s83, 0, 0x10000
	s_cmp_eq_u32 s12, 12
	s_cselect_b32 s25, s39, s22
	s_cselect_b32 s24, s73, s13
	s_cselect_b32 s23, s17, s82
	s_cselect_b32 s22, s76, s77
	s_add_i32 s13, 0, 0x14000
	v_add_u32_e32 v146, s83, v17
	v_add_u32_e32 v162, s13, v17
	ds_read_b128 v[134:137], v146
	ds_read_b128 v[138:141], v146 offset:1024
	ds_read_b128 v[142:145], v146 offset:2048
	ds_read_b128 v[146:149], v146 offset:3072
	ds_read_b128 v[150:153], v162
	ds_read_b128 v[154:157], v162 offset:1024
	ds_read_b128 v[158:161], v162 offset:2048
	ds_read_b128 v[162:165], v162 offset:3072
	v_lshl_add_u64 v[180:181], s[50:51], 0, v[172:173]
	s_add_i32 m0, s20, 0xc000
	ds_read_b128 v[176:179], v184
	ds_read_b128 v[186:189], v184 offset:1024
	ds_read_b128 v[190:193], v184 offset:2048
	ds_read_b128 v[194:197], v184 offset:3072
	ds_read_b128 v[198:201], v184 offset:4096
	ds_read_b128 v[202:205], v184 offset:5120
	ds_read_b128 v[206:209], v184 offset:6144
	ds_read_b128 v[210:213], v184 offset:7168
	global_load_lds_dwordx4 v[180:181], off
	v_lshl_add_u64 v[180:181], s[50:51], 0, v[174:175]
	s_add_i32 m0, s20, 0xe000
	s_nop 0
	global_load_lds_dwordx4 v[180:181], off
	s_cmp_lg_u32 s12, s32
	s_cbranch_scc1 .Lfw8_986_0
	s_waitcnt vmcnt(24)
	s_branch .Lfwd_986_0

; #define PG8_STAGE(bufoff, gbase, voff) do { _Pragma("unroll") for (int _i = 0; _i < 2; ++_i) \
;         __builtin_amdgcn_global_load_lds((const unsigned*)((const char*)(gbase) + (voff)[_i]), (PG8_LAS unsigned*)(lds + (bufoff) + ldsw + _i * 8192), 16, 0, 0); } while (0)
; #define PG8_LDA(dst, b, h) do { _Pragma("unroll") for (int m = 0; m < 4; ++m) _Pragma("unroll") for (int k = 0; k < 2; ++k) dst[m][k] = *(const PG8_LAS bf16x8*)(lds + PG8_SA(b, h) + aoff + m * 2048 + k * 1024); } while (0)
; #define PG8_MMA(ai, bj, At, Bt) do { __builtin_amdgcn_s_setprio(1); _Pragma("unroll") for (int m = 0; m < 4; ++m) _Pragma("unroll") for (int n = 0; n < 2; ++n) _Pragma("unroll") for (int k = 0; k < 2; ++k) \
;         acc[ai][bj][m][n] = __builtin_amdgcn_mfma_f32_16x16x32_f16(Bt[n][k], At[m][k], acc[ai][bj][m][n], 0, 0, 0); __builtin_amdgcn_s_setprio(0); } while (0)
; #define PG8_WAIT_V(n) asm volatile("s_waitcnt vmcnt(" #n ")" ::: "memory")
; #define PG8_WAIT_L(n) asm volatile("s_waitcnt lgkmcnt(" #n ")" ::: "memory")
; #define PG8_BAR __builtin_amdgcn_s_barrier()
; #define PG8_SCHED __builtin_amdgcn_sched_barrier(0)
; template <class Epi, class Sched, bool ALIGN_EPI = false, bool SP2 = false>
; __device__ __forceinline__ void gemm_phase(PG8_LAS unsigned char* lds, const Gemm g, const Sched& S, const Epi& E) {
;     ...
;             PG8_WAIT_V(8); PG8_WAIT_L(0); PG8_BAR; PG8_MMA(0, 0, At, B0); PG8_MMA(0, 1, At, B1); PG8_BAR; PG8_SCHED;
;             PG8_LDA(At, 0, 1); PG8_STAGE(PG8_SB(0, 0), b2, voffB); PG8_STAGE(PG8_SB(0, 1), b2 + hstep, voffB); PG8_STAGE(PG8_SA(0, 0), a2, voffA);
.Lfwd_986_0:
	s_waitcnt lgkmcnt(0)
	s_barrier
	v_mfma_f32_16x16x32_f16 v[130:133], v[134:137], v[176:179], v[130:133]
	v_mfma_f32_16x16x32_f16 v[126:129], v[142:145], v[176:179], v[126:129]
	v_mfma_f32_16x16x32_f16 v[114:117], v[134:137], v[190:193], v[114:117]
	v_mfma_f32_16x16x32_f16 v[110:113], v[142:145], v[190:193], v[110:113]
	v_mfma_f32_16x16x32_f16 v[98:101], v[134:137], v[198:201], v[98:101]
	v_mfma_f32_16x16x32_f16 v[94:97], v[142:145], v[198:201], v[94:97]
	v_mfma_f32_16x16x32_f16 v[82:85], v[134:137], v[206:209], v[82:85]
	v_mfma_f32_16x16x32_f16 v[78:81], v[142:145], v[206:209], v[78:81]
	v_mfma_f32_16x16x32_f16 v[130:133], v[138:141], v[186:189], v[130:133]
	v_mfma_f32_16x16x32_f16 v[126:129], v[146:149], v[186:189], v[126:129]
	v_mfma_f32_16x16x32_f16 v[114:117], v[138:141], v[194:197], v[114:117]
	v_mfma_f32_16x16x32_f16 v[110:113], v[146:149], v[194:197], v[110:113]
	v_mfma_f32_16x16x32_f16 v[98:101], v[138:141], v[202:205], v[98:101]
	v_mfma_f32_16x16x32_f16 v[94:97], v[146:149], v[202:205], v[94:97]
	v_mfma_f32_16x16x32_f16 v[82:85], v[138:141], v[210:213], v[82:85]
	v_mfma_f32_16x16x32_f16 v[78:81], v[146:149], v[210:213], v[78:81]
	v_mfma_f32_16x16x32_f16 v[122:125], v[150:153], v[176:179], v[122:125]
	v_mfma_f32_16x16x32_f16 v[118:121], v[158:161], v[176:179], v[118:121]
	v_mfma_f32_16x16x32_f16 v[106:109], v[150:153], v[190:193], v[106:109]
	v_mfma_f32_16x16x32_f16 v[102:105], v[158:161], v[190:193], v[102:105]
	v_mfma_f32_16x16x32_f16 v[90:93], v[150:153], v[198:201], v[90:93]
	v_mfma_f32_16x16x32_f16 v[86:89], v[158:161], v[198:201], v[86:89]
	v_mfma_f32_16x16x32_f16 v[74:77], v[150:153], v[206:209], v[74:77]
	v_mfma_f32_16x16x32_f16 v[70:73], v[158:161], v[206:209], v[70:73]
	v_mfma_f32_16x16x32_f16 v[122:125], v[154:157], v[186:189], v[122:125]
	v_mfma_f32_16x16x32_f16 v[118:121], v[162:165], v[186:189], v[118:121]
	v_mfma_f32_16x16x32_f16 v[106:109], v[154:157], v[194:197], v[106:109]
	v_mfma_f32_16x16x32_f16 v[102:105], v[162:165], v[194:197], v[102:105]
	v_mfma_f32_16x16x32_f16 v[90:93], v[154:157], v[202:205], v[90:93]
	v_mfma_f32_16x16x32_f16 v[86:89], v[162:165], v[202:205], v[86:89]
	v_mfma_f32_16x16x32_f16 v[74:77], v[154:157], v[210:213], v[74:77]
	v_mfma_f32_16x16x32_f16 v[70:73], v[162:165], v[210:213], v[70:73]
	s_barrier
	s_add_i32 s83, s83, s5
	v_lshl_add_u64 v[180:181], s[22:23], 0, v[168:169]
	s_mov_b32 m0, s83
	ds_read_b128 v[176:179], v184 offset:16384
	ds_read_b128 v[186:189], v184 offset:17408
	ds_read_b128 v[190:193], v184 offset:18432
	ds_read_b128 v[194:197], v184 offset:19456
	ds_read_b128 v[198:201], v184 offset:20480
	ds_read_b128 v[202:205], v184 offset:21504
	ds_read_b128 v[206:209], v184 offset:22528
	ds_read_b128 v[210:213], v184 offset:23552
	global_load_lds_dwordx4 v[180:181], off
	s_add_i32 m0, s83, 0x2000
	s_add_u32 s92, s22, 0x40000
	v_lshl_add_u64 v[214:215], s[22:23], 0, v[14:15]
	s_addc_u32 s93, s23, 0
	s_add_i32 s13, s13, s5
	global_load_lds_dwordx4 v[214:215], off
	v_lshl_add_u64 v[218:219], s[92:93], 0, v[168:169]
	s_mov_b32 m0, s13
	v_lshl_add_u64 v[220:221], s[24:25], 0, v[166:167]
	global_load_lds_dwordx4 v[218:219], off
	v_lshl_add_u64 v[218:219], s[92:93], 0, v[14:15]
	s_add_i32 m0, s13, 0x2000
	s_nop 0
	global_load_lds_dwordx4 v[218:219], off
	v_lshl_add_u64 v[218:219], s[24:25], 0, v[170:171]
	s_mov_b32 m0, s20
	s_nop 0
	global_load_lds_dwordx4 v[218:219], off
	s_mov_b32 m0, s26
	s_nop 0
	global_load_lds_dwordx4 v[220:221], off
	s_cmp_lg_u32 s12, s32
	s_cbranch_scc1 .Lfw8_986_1
	s_waitcnt vmcnt(24)
	s_branch .Lfwd_986_1

; #define PG8_STAGE(bufoff, gbase, voff) do { _Pragma("unroll") for (int _i = 0; _i < 2; ++_i) \
;         __builtin_amdgcn_global_load_lds((const unsigned*)((const char*)(gbase) + (voff)[_i]), (PG8_LAS unsigned*)(lds + (bufoff) + ldsw + _i * 8192), 16, 0, 0); } while (0)
; #define PG8_LDA(dst, b, h) do { _Pragma("unroll") for (int m = 0; m < 4; ++m) _Pragma("unroll") for (int k = 0; k < 2; ++k) dst[m][k] = *(const PG8_LAS bf16x8*)(lds + PG8_SA(b, h) + aoff + m * 2048 + k * 1024); } while (0)
; #define PG8_LDB(dst, b, h) do { _Pragma("unroll") for (int n = 0; n < 2; ++n) _Pragma("unroll") for (int k = 0; k < 2; ++k) dst[n][k] = *(const PG8_LAS bf16x8*)(lds + PG8_SB(b, h) + boff + n * 2048 + k * 1024); } while (0)
; #define PG8_MMA(ai, bj, At, Bt) do { __builtin_amdgcn_s_setprio(1); _Pragma("unroll") for (int m = 0; m < 4; ++m) _Pragma("unroll") for (int n = 0; n < 2; ++n) _Pragma("unroll") for (int k = 0; k < 2; ++k) \
;         acc[ai][bj][m][n] = __builtin_amdgcn_mfma_f32_16x16x32_f16(Bt[n][k], At[m][k], acc[ai][bj][m][n], 0, 0, 0); __builtin_amdgcn_s_setprio(0); } while (0)
; #define PG8_WAIT_V(n) asm volatile("s_waitcnt vmcnt(" #n ")" ::: "memory")
; #define PG8_WAIT_L(n) asm volatile("s_waitcnt lgkmcnt(" #n ")" ::: "memory")
; #define PG8_BAR __builtin_amdgcn_s_barrier()
; #define PG8_SCHED __builtin_amdgcn_sched_barrier(0)
; template <class Epi, class Sched, bool ALIGN_EPI = false, bool SP2 = false>
; __device__ __forceinline__ void gemm_phase(PG8_LAS unsigned char* lds, const Gemm g, const Sched& S, const Epi& E) {
;     ...
;             PG8_WAIT_V(8); PG8_WAIT_L(0); PG8_BAR; PG8_MMA(1, 0, At, B0); PG8_MMA(1, 1, At, B1); PG8_BAR; PG8_SCHED;
;             PG8_LDB(B0, 1, 0); PG8_LDB(B1, 1, 1); PG8_SCHED; PG8_LDA(At, 1, 0); PG8_STAGE(PG8_SA(0, 1), a2 + hstep, voffA);
;             PG8_WAIT_V(8); PG8_WAIT_L(0); PG8_BAR; PG8_MMA(0, 0, At, B0); PG8_MMA(0, 1, At, B1); PG8_BAR; PG8_SCHED;
.Lfwd_986_1:
	s_waitcnt lgkmcnt(0)
	s_barrier
	v_mfma_f32_16x16x32_f16 v[66:69], v[134:137], v[176:179], v[66:69]
	v_mfma_f32_16x16x32_f16 v[62:65], v[142:145], v[176:179], v[62:65]
	v_mfma_f32_16x16x32_f16 v[50:53], v[134:137], v[190:193], v[50:53]
	v_mfma_f32_16x16x32_f16 v[46:49], v[142:145], v[190:193], v[46:49]
	v_mfma_f32_16x16x32_f16 v[34:37], v[134:137], v[198:201], v[34:37]
	v_mfma_f32_16x16x32_f16 v[30:33], v[142:145], v[198:201], v[30:33]
	v_mfma_f32_16x16x32_f16 v[18:21], v[134:137], v[206:209], v[18:21]
	v_mfma_f32_16x16x32_f16 v[10:13], v[142:145], v[206:209], v[10:13]
	v_mfma_f32_16x16x32_f16 v[66:69], v[138:141], v[186:189], v[66:69]
	v_mfma_f32_16x16x32_f16 v[62:65], v[146:149], v[186:189], v[62:65]
	v_mfma_f32_16x16x32_f16 v[50:53], v[138:141], v[194:197], v[50:53]
	v_mfma_f32_16x16x32_f16 v[46:49], v[146:149], v[194:197], v[46:49]
	v_mfma_f32_16x16x32_f16 v[34:37], v[138:141], v[202:205], v[34:37]
	v_mfma_f32_16x16x32_f16 v[30:33], v[146:149], v[202:205], v[30:33]
	v_mfma_f32_16x16x32_f16 v[18:21], v[138:141], v[210:213], v[18:21]
	v_mfma_f32_16x16x32_f16 v[10:13], v[146:149], v[210:213], v[10:13]
	v_mfma_f32_16x16x32_f16 v[58:61], v[150:153], v[176:179], v[58:61]
	v_mfma_f32_16x16x32_f16 v[54:57], v[158:161], v[176:179], v[54:57]
	v_mfma_f32_16x16x32_f16 v[42:45], v[150:153], v[190:193], v[42:45]
	v_mfma_f32_16x16x32_f16 v[38:41], v[158:161], v[190:193], v[38:41]
	v_mfma_f32_16x16x32_f16 v[26:29], v[150:153], v[198:201], v[26:29]
	v_mfma_f32_16x16x32_f16 v[22:25], v[158:161], v[198:201], v[22:25]
	v_mfma_f32_16x16x32_f16 v[6:9], v[150:153], v[206:209], v[6:9]
	v_mfma_f32_16x16x32_f16 v[2:5], v[158:161], v[206:209], v[2:5]
	v_mfma_f32_16x16x32_f16 v[58:61], v[154:157], v[186:189], v[58:61]
	v_mfma_f32_16x16x32_f16 v[54:57], v[162:165], v[186:189], v[54:57]
	v_mfma_f32_16x16x32_f16 v[42:45], v[154:157], v[194:197], v[42:45]
	v_mfma_f32_16x16x32_f16 v[38:41], v[162:165], v[194:197], v[38:41]
	v_mfma_f32_16x16x32_f16 v[26:29], v[154:157], v[202:205], v[26:29]
	v_mfma_f32_16x16x32_f16 v[22:25], v[162:165], v[202:205], v[22:25]
	v_mfma_f32_16x16x32_f16 v[6:9], v[154:157], v[210:213], v[6:9]
	v_mfma_f32_16x16x32_f16 v[2:5], v[162:165], v[210:213], v[2:5]
	s_barrier
	s_add_i32 s13, 0, 0x18000
	s_add_i32 s83, 0, 0x1c000
	v_add_u32_e32 v146, s13, v17
	v_add_u32_e32 v162, s83, v17
	ds_read_b128 v[134:137], v146
	ds_read_b128 v[138:141], v146 offset:1024
	ds_read_b128 v[142:145], v146 offset:2048
	ds_read_b128 v[146:149], v146 offset:3072
	ds_read_b128 v[150:153], v162
	ds_read_b128 v[154:157], v162 offset:1024
	ds_read_b128 v[158:161], v162 offset:2048
	ds_read_b128 v[162:165], v162 offset:3072
	s_add_u32 s24, s24, 0x40000
	s_addc_u32 s25, s25, 0
	s_mov_b32 m0, s27
	v_lshl_add_u64 v[222:223], s[24:25], 0, v[170:171]
	ds_read_b128 v[176:179], v184 offset:32768
	ds_read_b128 v[186:189], v184 offset:33792
	ds_read_b128 v[190:193], v184 offset:34816
	ds_read_b128 v[194:197], v184 offset:35840
	ds_read_b128 v[198:201], v184 offset:36864
	ds_read_b128 v[202:205], v184 offset:37888
	ds_read_b128 v[206:209], v184 offset:38912
	ds_read_b128 v[210:213], v184 offset:39936
	global_load_lds_dwordx4 v[222:223], off
	v_lshl_add_u64 v[222:223], s[24:25], 0, v[166:167]
	s_mov_b32 m0, s28
	s_nop 0
	global_load_lds_dwordx4 v[222:223], off
	s_waitcnt vmcnt(8)
	s_waitcnt lgkmcnt(0)
	s_barrier
	v_mfma_f32_16x16x32_f16 v[130:133], v[134:137], v[176:179], v[130:133]
	v_mfma_f32_16x16x32_f16 v[126:129], v[142:145], v[176:179], v[126:129]
	v_mfma_f32_16x16x32_f16 v[114:117], v[134:137], v[190:193], v[114:117]
	v_mfma_f32_16x16x32_f16 v[110:113], v[142:145], v[190:193], v[110:113]
	v_mfma_f32_16x16x32_f16 v[98:101], v[134:137], v[198:201], v[98:101]
	v_mfma_f32_16x16x32_f16 v[94:97], v[142:145], v[198:201], v[94:97]
	v_mfma_f32_16x16x32_f16 v[82:85], v[134:137], v[206:209], v[82:85]
	v_mfma_f32_16x16x32_f16 v[78:81], v[142:145], v[206:209], v[78:81]
	v_mfma_f32_16x16x32_f16 v[130:133], v[138:141], v[186:189], v[130:133]
	v_mfma_f32_16x16x32_f16 v[126:129], v[146:149], v[186:189], v[126:129]
	v_mfma_f32_16x16x32_f16 v[114:117], v[138:141], v[194:197], v[114:117]
	v_mfma_f32_16x16x32_f16 v[110:113], v[146:149], v[194:197], v[110:113]
	v_mfma_f32_16x16x32_f16 v[98:101], v[138:141], v[202:205], v[98:101]
	v_mfma_f32_16x16x32_f16 v[94:97], v[146:149], v[202:205], v[94:97]
	v_mfma_f32_16x16x32_f16 v[82:85], v[138:141], v[210:213], v[82:85]
	v_mfma_f32_16x16x32_f16 v[78:81], v[146:149], v[210:213], v[78:81]
	v_mfma_f32_16x16x32_f16 v[122:125], v[150:153], v[176:179], v[122:125]
	v_mfma_f32_16x16x32_f16 v[118:121], v[158:161], v[176:179], v[118:121]
	v_mfma_f32_16x16x32_f16 v[106:109], v[150:153], v[190:193], v[106:109]
	v_mfma_f32_16x16x32_f16 v[102:105], v[158:161], v[190:193], v[102:105]
	v_mfma_f32_16x16x32_f16 v[90:93], v[150:153], v[198:201], v[90:93]
	v_mfma_f32_16x16x32_f16 v[86:89], v[158:161], v[198:201], v[86:89]
	v_mfma_f32_16x16x32_f16 v[74:77], v[150:153], v[206:209], v[74:77]
	v_mfma_f32_16x16x32_f16 v[70:73], v[158:161], v[206:209], v[70:73]
	v_mfma_f32_16x16x32_f16 v[122:125], v[154:157], v[186:189], v[122:125]
	v_mfma_f32_16x16x32_f16 v[118:121], v[162:165], v[186:189], v[118:121]
	v_mfma_f32_16x16x32_f16 v[106:109], v[154:157], v[194:197], v[106:109]
	v_mfma_f32_16x16x32_f16 v[102:105], v[162:165], v[194:197], v[102:105]
	v_mfma_f32_16x16x32_f16 v[90:93], v[154:157], v[202:205], v[90:93]
	v_mfma_f32_16x16x32_f16 v[86:89], v[162:165], v[202:205], v[86:89]
	v_mfma_f32_16x16x32_f16 v[74:77], v[154:157], v[210:213], v[74:77]
	v_mfma_f32_16x16x32_f16 v[70:73], v[162:165], v[210:213], v[70:73]
	s_barrier
; #define PG8_STAGE(bufoff, gbase, voff) do { _Pragma("unroll") for (int _i = 0; _i < 2; ++_i) \
;         __builtin_amdgcn_global_load_lds((const unsigned*)((const char*)(gbase) + (voff)[_i]), (PG8_LAS unsigned*)(lds + (bufoff) + ldsw + _i * 8192), 16, 0, 0); } while (0)
; #define PG8_LDA(dst, b, h) do { _Pragma("unroll") for (int m = 0; m < 4; ++m) _Pragma("unroll") for (int k = 0; k < 2; ++k) dst[m][k] = *(const PG8_LAS bf16x8*)(lds + PG8_SA(b, h) + aoff + m * 2048 + k * 1024); } while (0)
; #define PG8_MMA(ai, bj, At, Bt) do { __builtin_amdgcn_s_setprio(1); _Pragma("unroll") for (int m = 0; m < 4; ++m) _Pragma("unroll") for (int n = 0; n < 2; ++n) _Pragma("unroll") for (int k = 0; k < 2; ++k) \
;         acc[ai][bj][m][n] = __builtin_amdgcn_mfma_f32_16x16x32_f16(Bt[n][k], At[m][k], acc[ai][bj][m][n], 0, 0, 0); __builtin_amdgcn_s_setprio(0); } while (0)
; #define PG8_WAIT_V(n) asm volatile("s_waitcnt vmcnt(" #n ")" ::: "memory")
; #define PG8_WAIT_L(n) asm volatile("s_waitcnt lgkmcnt(" #n ")" ::: "memory")
; #define PG8_BAR __builtin_amdgcn_s_barrier()
; #define PG8_SCHED __builtin_amdgcn_sched_barrier(0)
; template <class Epi, class Sched, bool ALIGN_EPI = false, bool SP2 = false>
; __device__ __forceinline__ void gemm_phase(PG8_LAS unsigned char* lds, const Gemm g, const Sched& S, const Epi& E) {
;     ...
;             PG8_LDA(At, 1, 1); PG8_STAGE(PG8_SB(1, 0), b3, voffB); PG8_STAGE(PG8_SB(1, 1), b3 + hstep, voffB); PG8_STAGE(PG8_SA(1, 0), a3, voffA);
;             PG8_WAIT_V(8); PG8_WAIT_L(0); PG8_BAR; PG8_MMA(1, 0, At, B0); PG8_MMA(1, 1, At, B1); PG8_BAR; PG8_SCHED;
	s_add_i32 s13, s13, s5
	v_lshl_add_u64 v[180:181], v[180:181], 0, s[34:35]
	s_mov_b32 m0, s13
	ds_read_b128 v[176:179], v184 offset:49152
	ds_read_b128 v[186:189], v184 offset:50176
	ds_read_b128 v[190:193], v184 offset:51200
	ds_read_b128 v[194:197], v184 offset:52224
	ds_read_b128 v[198:201], v184 offset:53248
	ds_read_b128 v[202:205], v184 offset:54272
	ds_read_b128 v[206:209], v184 offset:55296
	ds_read_b128 v[210:213], v184 offset:56320
	global_load_lds_dwordx4 v[180:181], off
	s_add_i32 m0, s13, 0x2000
	s_add_u32 s22, s22, 0x40080
	v_lshl_add_u64 v[180:181], v[214:215], 0, s[34:35]
	s_addc_u32 s23, s23, 0
	s_add_i32 s13, s83, s5
	global_load_lds_dwordx4 v[180:181], off
	v_lshl_add_u64 v[180:181], s[22:23], 0, v[168:169]
	s_mov_b32 m0, s13
	s_nop 0
	global_load_lds_dwordx4 v[180:181], off
	v_lshl_add_u64 v[180:181], s[22:23], 0, v[14:15]
	s_add_i32 m0, s13, 0x2000
	s_nop 0
	global_load_lds_dwordx4 v[180:181], off
	v_lshl_add_u64 v[180:181], v[218:219], 0, s[34:35]
	s_mov_b32 m0, s29
	s_nop 0
	global_load_lds_dwordx4 v[180:181], off
	v_lshl_add_u64 v[180:181], v[220:221], 0, s[34:35]
	s_mov_b32 m0, s33
	s_nop 0
	global_load_lds_dwordx4 v[180:181], off
	s_waitcnt vmcnt(8)
	s_waitcnt lgkmcnt(0)
	s_barrier
	v_mfma_f32_16x16x32_f16 v[66:69], v[134:137], v[176:179], v[66:69]
	v_mfma_f32_16x16x32_f16 v[62:65], v[142:145], v[176:179], v[62:65]
	v_mfma_f32_16x16x32_f16 v[50:53], v[134:137], v[190:193], v[50:53]
	v_mfma_f32_16x16x32_f16 v[46:49], v[142:145], v[190:193], v[46:49]
	v_mfma_f32_16x16x32_f16 v[34:37], v[134:137], v[198:201], v[34:37]
	v_mfma_f32_16x16x32_f16 v[30:33], v[142:145], v[198:201], v[30:33]
	v_mfma_f32_16x16x32_f16 v[18:21], v[134:137], v[206:209], v[18:21]
	v_mfma_f32_16x16x32_f16 v[10:13], v[142:145], v[206:209], v[10:13]
	v_mfma_f32_16x16x32_f16 v[66:69], v[138:141], v[186:189], v[66:69]
	v_mfma_f32_16x16x32_f16 v[62:65], v[146:149], v[186:189], v[62:65]
	v_mfma_f32_16x16x32_f16 v[50:53], v[138:141], v[194:197], v[50:53]
	v_mfma_f32_16x16x32_f16 v[46:49], v[146:149], v[194:197], v[46:49]
	v_mfma_f32_16x16x32_f16 v[34:37], v[138:141], v[202:205], v[34:37]
	v_mfma_f32_16x16x32_f16 v[30:33], v[146:149], v[202:205], v[30:33]
	v_mfma_f32_16x16x32_f16 v[18:21], v[138:141], v[210:213], v[18:21]
	v_mfma_f32_16x16x32_f16 v[10:13], v[146:149], v[210:213], v[10:13]
	v_mfma_f32_16x16x32_f16 v[58:61], v[150:153], v[176:179], v[58:61]
	v_mfma_f32_16x16x32_f16 v[54:57], v[158:161], v[176:179], v[54:57]
	v_mfma_f32_16x16x32_f16 v[42:45], v[150:153], v[190:193], v[42:45]
	v_mfma_f32_16x16x32_f16 v[38:41], v[158:161], v[190:193], v[38:41]
	v_mfma_f32_16x16x32_f16 v[26:29], v[150:153], v[198:201], v[26:29]
	v_mfma_f32_16x16x32_f16 v[22:25], v[158:161], v[198:201], v[22:25]
	v_mfma_f32_16x16x32_f16 v[6:9], v[150:153], v[206:209], v[6:9]
	v_mfma_f32_16x16x32_f16 v[2:5], v[158:161], v[206:209], v[2:5]
	v_mfma_f32_16x16x32_f16 v[58:61], v[154:157], v[186:189], v[58:61]
	v_mfma_f32_16x16x32_f16 v[54:57], v[162:165], v[186:189], v[54:57]
	v_mfma_f32_16x16x32_f16 v[42:45], v[154:157], v[194:197], v[42:45]
	v_mfma_f32_16x16x32_f16 v[38:41], v[162:165], v[194:197], v[38:41]
	v_mfma_f32_16x16x32_f16 v[26:29], v[154:157], v[202:205], v[26:29]
	v_mfma_f32_16x16x32_f16 v[22:25], v[162:165], v[202:205], v[22:25]
	v_mfma_f32_16x16x32_f16 v[6:9], v[154:157], v[210:213], v[6:9]
	v_mfma_f32_16x16x32_f16 v[2:5], v[162:165], v[210:213], v[2:5]
	s_barrier
	s_add_i32 s12, s12, 2
	s_add_u32 s50, s50, 0x100
	s_addc_u32 s51, s51, 0
	s_add_u32 s77, s77, 0x100
	s_addc_u32 s82, s82, 0
	s_cmp_gt_u32 s12, 13
	s_cbranch_scc0 .LBB0_986
	s_and_b64 vcc, exec, s[14:15]
	s_cbranch_vccz .LBB0_989
	s_barrier

; #define PG8_STAGE(bufoff, gbase, voff) do { _Pragma("unroll") for (int _i = 0; _i < 2; ++_i) \
;         __builtin_amdgcn_global_load_lds((const unsigned*)((const char*)(gbase) + (voff)[_i]), (PG8_LAS unsigned*)(lds + (bufoff) + ldsw + _i * 8192), 16, 0, 0); } while (0)
; #define PG8_WAIT_V(n) asm volatile("s_waitcnt vmcnt(" #n ")" ::: "memory")
; #define PG8_BAR __builtin_amdgcn_s_barrier()
; template <class Epi, class Sched, bool ALIGN_EPI = false, bool SP2 = false>
; __device__ __forceinline__ void gemm_phase(PG8_LAS unsigned char* lds, const Gemm g, const Sched& S, const Epi& E) {
;     ...
;     for (int i = 0; i < 2; ++i) { int R, C; stage_rc(tid * 16 + i * 8192, R, C); const int Rb = Epi::PERM ? ((R & ~31) + perm32(R & 31)) : R;
;         voffA[i] = (unsigned)(R * K + C) * 2u; voffB[i] = (unsigned)(Rb * K + C) * 2u; }
;     const size_t kstep = (size_t)(BK * 2);
;     const size_t hstep = (size_t)HALF * K * 2;
;     const size_t tstep = 2 * hstep;
;     const unsigned ldsw = (unsigned)wid * 1024u;
;     const int aoff = lds_byte(wr * 64 + fr, fq * 8), boff = lds_byte(wc * 32 + fr, fq * 8);
;     ...
;     if constexpr (SP2) {
;         PG8_STAGE(PG8_SB(0, 0), cB, voffB); PG8_STAGE(PG8_SB(0, 1), cB + hstep, voffB); PG8_STAGE(PG8_SA(0, 0), cA, voffA); PG8_STAGE(PG8_SA(0, 1), cA + hstep, voffA);
;         if (wr == 1) PG8_BAR;
;         PG8_WAIT_V(2); PG8_BAR;
;         PG8_STAGE(PG8_SB(1, 0), cB + kstep, voffB); PG8_STAGE(PG8_SA(1, 0), cA + kstep, voffA); PG8_STAGE(PG8_SB(1, 1), cB + hstep + kstep, voffB);
;         PG8_WAIT_V(6); PG8_BAR;
.LBB0_1124:
	v_bfe_u32 v20, v11, 4, 2
	v_readlane_b32 s38, v255, 3
	v_and_b32_e32 v21, 15, v11
	v_lshlrev_b32_e32 v23, 4, v20
	v_lshlrev_b32_e32 v11, 2, v11
	v_mov_b32_e32 v195, v0
	v_readlane_b32 s39, v255, 4
	s_and_b32 s71, s17, 3
	v_lshl_or_b32 v23, v21, 6, v23
	s_lshl_b32 s13, s12, 13
	v_and_b32_e32 v11, 32, v11
	s_add_i32 m0, s11, 0x18000
	v_lshl_add_u64 v[2:3], v[2:3], 0, s[34:35]
	v_lshl_add_u64 v[12:13], s[38:39], 0, v[194:195]
	v_mov_b32_e32 v191, v0
	v_bitop3_b32 v24, v23, s13, v11 bitop3:0xde
	s_lshl_b32 s13, s71, 12
	s_waitcnt vmcnt(2)
	s_barrier
	global_load_lds_dwordx4 v[2:3], off
	v_lshl_add_u64 v[2:3], v[4:5], 0, s[34:35]
	s_add_i32 m0, s11, 0x1a000
	s_add_i32 s72, s11, 0x8000
	s_add_i32 s73, s11, 0xa000
	v_lshl_add_u64 v[18:19], s[38:39], 0, v[190:191]
	global_load_lds_dwordx4 v[2:3], off
	v_lshl_add_u64 v[2:3], v[12:13], 0, s[34:35]
	s_mov_b32 m0, s72
	s_add_u32 s24, s22, 0x100080
	global_load_lds_dwordx4 v[2:3], off
	v_lshl_add_u64 v[2:3], v[18:19], 0, s[34:35]
	s_mov_b32 m0, s73
	s_addc_u32 s25, s23, 0
	global_load_lds_dwordx4 v[2:3], off
	s_add_i32 m0, s11, 0x1c000
	v_lshl_add_u64 v[2:3], s[24:25], 0, v[192:193]
	global_load_lds_dwordx4 v[2:3], off
	v_lshl_add_u64 v[2:3], s[24:25], 0, v[14:15]
	s_add_i32 m0, s11, 0x1e000
	s_cmpk_lt_u32 s16, 0x100
	global_load_lds_dwordx4 v[2:3], off
	v_lshlrev_b32_e32 v2, 16, v9
	v_and_b32_e32 v2, 0xfffe0000, v2
	v_lshl_add_u32 v2, v8, 13, v2
	v_and_b32_e32 v3, 1, v9
	v_lshl_or_b32 v2, v3, 6, v2
	v_lshl_or_b32 v17, s12, 6, v21
	s_cselect_b64 s[40:41], -1, 0
	s_lshl_b32 s12, s12, 9
	v_lshl_add_u32 v196, v10, 1, v2
	v_lshlrev_b32_e32 v2, 16, v1
	s_add_i32 s12, s12, 0
	v_and_b32_e32 v2, 0xfffe0000, v2
	s_waitcnt vmcnt(6)
	s_add_i32 s12, s12, 0x20000
	v_lshl_add_u32 v2, v6, 13, v2
	v_and_b32_e32 v1, 1, v1
	v_lshlrev_b32_e32 v22, 3, v20
	v_bitop3_b32 v222, v23, s13, v11 bitop3:0xde
	v_lshl_add_u32 v224, v21, 3, s12
	v_lshl_or_b32 v1, v1, 6, v2
	v_readlane_b32 s12, v255, 1
	s_mov_b32 s26, 0
	v_cmp_eq_u32_e64 s[36:37], 0, v20
	v_lshl_or_b32 v223, s71, 5, v22
	v_mov_b32_e32 v197, v0
	v_lshl_add_u32 v198, v7, 1, v1
	v_mov_b32_e32 v199, v0
	v_add_u32_e32 v225, 0, v24
	v_readlane_b32 s20, v254, 30
	s_mov_b32 s27, s12
	s_mov_b64 s[24:25], s[38:39]
	s_barrier
	v_readlane_b32 s13, v255, 2
	s_mov_b32 s32, 1
	s_branch .LBB0_1127

; #define PG8_BAR __builtin_amdgcn_s_barrier()
; template <class Epi, class Sched, bool ALIGN_EPI = false, bool SP2 = false>
; __device__ __forceinline__ void gemm_phase(PG8_LAS unsigned char* lds, const Gemm g, const Sched& S, const Epi& E) {
;     ...
;         if (!has_next) break;
; #pragma unroll
;         for (int a = 0; a < 2; ++a)
; #pragma unroll
;             for (int b = 0; b < 2; ++b)
; #pragma unroll
;                 for (int m = 0; m < 4; ++m)
; #pragma unroll
;                     for (int n = 0; n < 2; ++n) acc[a][b][m][n] = (f32x4){0.f, 0.f, 0.f, 0.f};
;         cur = nxt; cA = nA; cB = nB; ++ui;
;         if constexpr (ALIGN_EPI) { if (wr == 1) PG8_BAR; }
.LBB0_1126:
	s_mov_b32 s32, -2
	s_andn2_b64 vcc, exec, s[22:23]
	s_mov_b32 s20, s42
	s_mov_b32 s27, s50
	s_mov_b64 s[22:23], s[16:17]
	s_mov_b64 s[24:25], s[82:83]
	s_mov_b32 s26, s75
	s_cbranch_vccz .LBB0_1158

; #define PG8_STAGE(bufoff, gbase, voff) do { _Pragma("unroll") for (int _i = 0; _i < 2; ++_i) \
;         __builtin_amdgcn_global_load_lds((const unsigned*)((const char*)(gbase) + (voff)[_i]), (PG8_LAS unsigned*)(lds + (bufoff) + ldsw + _i * 8192), 16, 0, 0); } while (0)
; #define PG8_LDA(dst, b, h) do { _Pragma("unroll") for (int m = 0; m < 4; ++m) _Pragma("unroll") for (int k = 0; k < 2; ++k) dst[m][k] = *(const PG8_LAS bf16x8*)(lds + PG8_SA(b, h) + aoff + m * 2048 + k * 1024); } while (0)
; #define PG8_LDB(dst, b, h) do { _Pragma("unroll") for (int n = 0; n < 2; ++n) _Pragma("unroll") for (int k = 0; k < 2; ++k) dst[n][k] = *(const PG8_LAS bf16x8*)(lds + PG8_SB(b, h) + boff + n * 2048 + k * 1024); } while (0)
; #define PG8_SCHED __builtin_amdgcn_sched_barrier(0)
; template <class Epi, class Sched, bool ALIGN_EPI = false, bool SP2 = false>
; __device__ __forceinline__ void gemm_phase(PG8_LAS unsigned char* lds, const Gemm g, const Sched& S, const Epi& E) {
;     ...
;             const bool last = (t == nt - 2);
;             const char* a1 = cA + (size_t)(t + 1) * kstep;
;             const char* a2 = last ? nA : cA + (size_t)(t + 2) * kstep; const char* b2 = last ? nB : cB + (size_t)(t + 2) * kstep;
;             const char* a3 = a2 + kstep; const char* b3 = b2 + kstep;
;             if (last && has_next) S.a_ready(nxt);
;             if constexpr (SP2) {
;             PG8_LDB(B0, 0, 0); PG8_LDB(B1, 0, 1); PG8_SCHED; PG8_LDA(At, 0, 0); PG8_STAGE(PG8_SA(1, 1), a1 + hstep, voffA);
.LBB0_1134:
	s_add_u32 s13, vcc_lo, 0xfff00080
	s_addc_u32 s22, vcc_hi, -1
	s_add_i32 s92, 0, 0x10000
	s_cmp_eq_u32 s12, 60
	s_cselect_b32 s25, s29, s22
	s_cselect_b32 s24, s51, s13
	v_add_u32_e32 v1, s92, v222
	s_cselect_b32 s23, s43, s77
	s_cselect_b32 s22, s58, s76
	s_add_i32 s13, 0, 0x14000
	ds_read_b128 v[66:69], v1
	ds_read_b128 v[70:73], v1 offset:1024
	ds_read_b128 v[78:81], v1 offset:2048
	ds_read_b128 v[82:85], v1 offset:3072
	v_add_u32_e32 v1, s13, v222
	ds_read_b128 v[86:89], v1
	ds_read_b128 v[90:93], v1 offset:1024
	ds_read_b128 v[94:97], v1 offset:2048
	ds_read_b128 v[98:101], v1 offset:3072
	v_lshl_add_u64 v[208:209], vcc, 0, v[196:197]
	s_add_i32 m0, s11, 0xc000
	ds_read_b128 v[158:161], v225
	ds_read_b128 v[170:173], v225 offset:1024
	ds_read_b128 v[174:177], v225 offset:2048
	ds_read_b128 v[178:181], v225 offset:3072
	ds_read_b128 v[182:185], v225 offset:4096
	ds_read_b128 v[186:189], v225 offset:5120
	ds_read_b128 v[200:203], v225 offset:6144
	ds_read_b128 v[204:207], v225 offset:7168
	global_load_lds_dwordx4 v[208:209], off
	v_lshl_add_u64 v[208:209], vcc, 0, v[198:199]
	s_add_i32 m0, s11, 0xe000
	s_nop 0
	global_load_lds_dwordx4 v[208:209], off
	s_cmp_lg_u32 s12, s32
	s_cbranch_scc1 .Lfw8_1134_0
	s_waitcnt vmcnt(40)
	s_branch .Lfwd_1134_0

; #define PG8_STAGE(bufoff, gbase, voff) do { _Pragma("unroll") for (int _i = 0; _i < 2; ++_i) \
;         __builtin_amdgcn_global_load_lds((const unsigned*)((const char*)(gbase) + (voff)[_i]), (PG8_LAS unsigned*)(lds + (bufoff) + ldsw + _i * 8192), 16, 0, 0); } while (0)
; #define PG8_LDA(dst, b, h) do { _Pragma("unroll") for (int m = 0; m < 4; ++m) _Pragma("unroll") for (int k = 0; k < 2; ++k) dst[m][k] = *(const PG8_LAS bf16x8*)(lds + PG8_SA(b, h) + aoff + m * 2048 + k * 1024); } while (0)
; #define PG8_MMA(ai, bj, At, Bt) do { __builtin_amdgcn_s_setprio(1); _Pragma("unroll") for (int m = 0; m < 4; ++m) _Pragma("unroll") for (int n = 0; n < 2; ++n) _Pragma("unroll") for (int k = 0; k < 2; ++k) \
;         acc[ai][bj][m][n] = __builtin_amdgcn_mfma_f32_16x16x32_f16(Bt[n][k], At[m][k], acc[ai][bj][m][n], 0, 0, 0); __builtin_amdgcn_s_setprio(0); } while (0)
; #define PG8_WAIT_V(n) asm volatile("s_waitcnt vmcnt(" #n ")" ::: "memory")
; #define PG8_WAIT_L(n) asm volatile("s_waitcnt lgkmcnt(" #n ")" ::: "memory")
; #define PG8_BAR __builtin_amdgcn_s_barrier()
; #define PG8_SCHED __builtin_amdgcn_sched_barrier(0)
; template <class Epi, class Sched, bool ALIGN_EPI = false, bool SP2 = false>
; __device__ __forceinline__ void gemm_phase(PG8_LAS unsigned char* lds, const Gemm g, const Sched& S, const Epi& E) {
;     ...
;             PG8_WAIT_V(8); PG8_WAIT_L(0); PG8_BAR; PG8_MMA(0, 0, At, B0); PG8_MMA(0, 1, At, B1); PG8_BAR; PG8_SCHED;
;             PG8_LDA(At, 0, 1); PG8_STAGE(PG8_SB(0, 0), b2, voffB); PG8_STAGE(PG8_SB(0, 1), b2 + hstep, voffB); PG8_STAGE(PG8_SA(0, 0), a2, voffA);
.Lfwd_1134_0:
	s_waitcnt lgkmcnt(0)
	s_barrier
	v_mfma_f32_16x16x32_f16 v[166:169], v[66:69], v[158:161], v[166:169]
	v_mfma_f32_16x16x32_f16 v[162:165], v[78:81], v[158:161], v[162:165]
	v_mfma_f32_16x16x32_f16 v[146:149], v[66:69], v[174:177], v[146:149]
	v_mfma_f32_16x16x32_f16 v[142:145], v[78:81], v[174:177], v[142:145]
	v_mfma_f32_16x16x32_f16 v[130:133], v[66:69], v[182:185], v[130:133]
	v_mfma_f32_16x16x32_f16 v[126:129], v[78:81], v[182:185], v[126:129]
	v_mfma_f32_16x16x32_f16 v[114:117], v[66:69], v[200:203], v[114:117]
	v_mfma_f32_16x16x32_f16 v[110:113], v[78:81], v[200:203], v[110:113]
	v_mfma_f32_16x16x32_f16 v[166:169], v[70:73], v[170:173], v[166:169]
	v_mfma_f32_16x16x32_f16 v[162:165], v[82:85], v[170:173], v[162:165]
	v_mfma_f32_16x16x32_f16 v[146:149], v[70:73], v[178:181], v[146:149]
	v_mfma_f32_16x16x32_f16 v[142:145], v[82:85], v[178:181], v[142:145]
	v_mfma_f32_16x16x32_f16 v[130:133], v[70:73], v[186:189], v[130:133]
	v_mfma_f32_16x16x32_f16 v[126:129], v[82:85], v[186:189], v[126:129]
	v_mfma_f32_16x16x32_f16 v[114:117], v[70:73], v[204:207], v[114:117]
	v_mfma_f32_16x16x32_f16 v[110:113], v[82:85], v[204:207], v[110:113]
	v_mfma_f32_16x16x32_f16 v[154:157], v[86:89], v[158:161], v[154:157]
	v_mfma_f32_16x16x32_f16 v[150:153], v[94:97], v[158:161], v[150:153]
	v_mfma_f32_16x16x32_f16 v[138:141], v[86:89], v[174:177], v[138:141]
	v_mfma_f32_16x16x32_f16 v[134:137], v[94:97], v[174:177], v[134:137]
	v_mfma_f32_16x16x32_f16 v[122:125], v[86:89], v[182:185], v[122:125]
	v_mfma_f32_16x16x32_f16 v[118:121], v[94:97], v[182:185], v[118:121]
	v_mfma_f32_16x16x32_f16 v[106:109], v[86:89], v[200:203], v[106:109]
	v_mfma_f32_16x16x32_f16 v[102:105], v[94:97], v[200:203], v[102:105]
	v_mfma_f32_16x16x32_f16 v[154:157], v[90:93], v[170:173], v[154:157]
	v_mfma_f32_16x16x32_f16 v[150:153], v[98:101], v[170:173], v[150:153]
	v_mfma_f32_16x16x32_f16 v[138:141], v[90:93], v[178:181], v[138:141]
	v_mfma_f32_16x16x32_f16 v[134:137], v[98:101], v[178:181], v[134:137]
	v_mfma_f32_16x16x32_f16 v[122:125], v[90:93], v[186:189], v[122:125]
	v_mfma_f32_16x16x32_f16 v[118:121], v[98:101], v[186:189], v[118:121]
	v_mfma_f32_16x16x32_f16 v[106:109], v[90:93], v[204:207], v[106:109]
	v_mfma_f32_16x16x32_f16 v[102:105], v[98:101], v[204:207], v[102:105]
	s_barrier
	s_add_i32 s92, s92, s5
	v_lshl_add_u64 v[208:209], s[22:23], 0, v[192:193]
	s_mov_b32 m0, s92
	ds_read_b128 v[158:161], v225 offset:16384
	ds_read_b128 v[170:173], v225 offset:17408
	ds_read_b128 v[174:177], v225 offset:18432
	ds_read_b128 v[178:181], v225 offset:19456
	ds_read_b128 v[182:185], v225 offset:20480
	ds_read_b128 v[186:189], v225 offset:21504
	ds_read_b128 v[200:203], v225 offset:22528
	ds_read_b128 v[204:207], v225 offset:23552
	global_load_lds_dwordx4 v[208:209], off
	s_add_i32 m0, s92, 0x2000
	s_add_u32 s92, s22, 0x100000
	v_lshl_add_u64 v[210:211], s[22:23], 0, v[14:15]
	s_addc_u32 s93, s23, 0
	s_add_i32 s13, s13, s5
	global_load_lds_dwordx4 v[210:211], off
	v_lshl_add_u64 v[212:213], s[92:93], 0, v[192:193]
	s_mov_b32 m0, s13
	v_lshl_add_u64 v[214:215], s[24:25], 0, v[190:191]
	global_load_lds_dwordx4 v[212:213], off
	v_lshl_add_u64 v[212:213], s[92:93], 0, v[14:15]
	s_add_i32 m0, s13, 0x2000
	s_nop 0
	global_load_lds_dwordx4 v[212:213], off
	v_lshl_add_u64 v[212:213], s[24:25], 0, v[194:195]
	s_mov_b32 m0, s11
	s_nop 0
	global_load_lds_dwordx4 v[212:213], off
	s_mov_b32 m0, s28
	s_nop 0
	global_load_lds_dwordx4 v[214:215], off
	s_cmp_lg_u32 s12, s32
	s_cbranch_scc1 .Lfw8_1134_1
	s_waitcnt vmcnt(40)
	s_branch .Lfwd_1134_1

; #define PG8_STAGE(bufoff, gbase, voff) do { _Pragma("unroll") for (int _i = 0; _i < 2; ++_i) \
;         __builtin_amdgcn_global_load_lds((const unsigned*)((const char*)(gbase) + (voff)[_i]), (PG8_LAS unsigned*)(lds + (bufoff) + ldsw + _i * 8192), 16, 0, 0); } while (0)
; #define PG8_LDA(dst, b, h) do { _Pragma("unroll") for (int m = 0; m < 4; ++m) _Pragma("unroll") for (int k = 0; k < 2; ++k) dst[m][k] = *(const PG8_LAS bf16x8*)(lds + PG8_SA(b, h) + aoff + m * 2048 + k * 1024); } while (0)
; #define PG8_LDB(dst, b, h) do { _Pragma("unroll") for (int n = 0; n < 2; ++n) _Pragma("unroll") for (int k = 0; k < 2; ++k) dst[n][k] = *(const PG8_LAS bf16x8*)(lds + PG8_SB(b, h) + boff + n * 2048 + k * 1024); } while (0)
; #define PG8_MMA(ai, bj, At, Bt) do { __builtin_amdgcn_s_setprio(1); _Pragma("unroll") for (int m = 0; m < 4; ++m) _Pragma("unroll") for (int n = 0; n < 2; ++n) _Pragma("unroll") for (int k = 0; k < 2; ++k) \
;         acc[ai][bj][m][n] = __builtin_amdgcn_mfma_f32_16x16x32_f16(Bt[n][k], At[m][k], acc[ai][bj][m][n], 0, 0, 0); __builtin_amdgcn_s_setprio(0); } while (0)
; #define PG8_WAIT_V(n) asm volatile("s_waitcnt vmcnt(" #n ")" ::: "memory")
; #define PG8_WAIT_L(n) asm volatile("s_waitcnt lgkmcnt(" #n ")" ::: "memory")
; #define PG8_BAR __builtin_amdgcn_s_barrier()
; #define PG8_SCHED __builtin_amdgcn_sched_barrier(0)
; template <class Epi, class Sched, bool ALIGN_EPI = false, bool SP2 = false>
; __device__ __forceinline__ void gemm_phase(PG8_LAS unsigned char* lds, const Gemm g, const Sched& S, const Epi& E) {
;     ...
;             PG8_WAIT_V(8); PG8_WAIT_L(0); PG8_BAR; PG8_MMA(1, 0, At, B0); PG8_MMA(1, 1, At, B1); PG8_BAR; PG8_SCHED;
;             PG8_LDB(B0, 1, 0); PG8_LDB(B1, 1, 1); PG8_SCHED; PG8_LDA(At, 1, 0); PG8_STAGE(PG8_SA(0, 1), a2 + hstep, voffA);
;             PG8_WAIT_V(8); PG8_WAIT_L(0); PG8_BAR; PG8_MMA(0, 0, At, B0); PG8_MMA(0, 1, At, B1); PG8_BAR; PG8_SCHED;
.Lfwd_1134_1:
	s_waitcnt lgkmcnt(0)
	s_barrier
	v_mfma_f32_16x16x32_f16 v[74:77], v[66:69], v[158:161], v[74:77]
	v_mfma_f32_16x16x32_f16 v[62:65], v[78:81], v[158:161], v[62:65]
	v_mfma_f32_16x16x32_f16 v[50:53], v[66:69], v[174:177], v[50:53]
	v_mfma_f32_16x16x32_f16 v[46:49], v[78:81], v[174:177], v[46:49]
	v_mfma_f32_16x16x32_f16 v[34:37], v[66:69], v[182:185], v[34:37]
	v_mfma_f32_16x16x32_f16 v[30:33], v[78:81], v[182:185], v[30:33]
	v_mfma_f32_16x16x32_f16 v[18:21], v[66:69], v[200:203], v[18:21]
	v_mfma_f32_16x16x32_f16 v[10:13], v[78:81], v[200:203], v[10:13]
	v_mfma_f32_16x16x32_f16 v[74:77], v[70:73], v[170:173], v[74:77]
	v_mfma_f32_16x16x32_f16 v[62:65], v[82:85], v[170:173], v[62:65]
	v_mfma_f32_16x16x32_f16 v[50:53], v[70:73], v[178:181], v[50:53]
	v_mfma_f32_16x16x32_f16 v[46:49], v[82:85], v[178:181], v[46:49]
	v_mfma_f32_16x16x32_f16 v[34:37], v[70:73], v[186:189], v[34:37]
	v_mfma_f32_16x16x32_f16 v[30:33], v[82:85], v[186:189], v[30:33]
	v_mfma_f32_16x16x32_f16 v[18:21], v[70:73], v[204:207], v[18:21]
	v_mfma_f32_16x16x32_f16 v[10:13], v[82:85], v[204:207], v[10:13]
	v_mfma_f32_16x16x32_f16 v[58:61], v[86:89], v[158:161], v[58:61]
	v_mfma_f32_16x16x32_f16 v[54:57], v[94:97], v[158:161], v[54:57]
	v_mfma_f32_16x16x32_f16 v[42:45], v[86:89], v[174:177], v[42:45]
	v_mfma_f32_16x16x32_f16 v[38:41], v[94:97], v[174:177], v[38:41]
	v_mfma_f32_16x16x32_f16 v[26:29], v[86:89], v[182:185], v[26:29]
	v_mfma_f32_16x16x32_f16 v[22:25], v[94:97], v[182:185], v[22:25]
	v_mfma_f32_16x16x32_f16 v[6:9], v[86:89], v[200:203], v[6:9]
	v_mfma_f32_16x16x32_f16 v[2:5], v[94:97], v[200:203], v[2:5]
	v_mfma_f32_16x16x32_f16 v[58:61], v[90:93], v[170:173], v[58:61]
	v_mfma_f32_16x16x32_f16 v[54:57], v[98:101], v[170:173], v[54:57]
	v_mfma_f32_16x16x32_f16 v[42:45], v[90:93], v[178:181], v[42:45]
	v_mfma_f32_16x16x32_f16 v[38:41], v[98:101], v[178:181], v[38:41]
	v_mfma_f32_16x16x32_f16 v[26:29], v[90:93], v[186:189], v[26:29]
	v_mfma_f32_16x16x32_f16 v[22:25], v[98:101], v[186:189], v[22:25]
	v_mfma_f32_16x16x32_f16 v[6:9], v[90:93], v[204:207], v[6:9]
	v_mfma_f32_16x16x32_f16 v[2:5], v[98:101], v[204:207], v[2:5]
	s_barrier
	s_add_i32 s13, 0, 0x18000
	v_add_u32_e32 v1, s13, v222
	s_add_i32 s92, 0, 0x1c000
	ds_read_b128 v[66:69], v1
	ds_read_b128 v[70:73], v1 offset:1024
	ds_read_b128 v[78:81], v1 offset:2048
	ds_read_b128 v[82:85], v1 offset:3072
	v_add_u32_e32 v1, s92, v222
	ds_read_b128 v[86:89], v1
	ds_read_b128 v[90:93], v1 offset:1024
	ds_read_b128 v[94:97], v1 offset:2048
	ds_read_b128 v[98:101], v1 offset:3072
	s_add_u32 s24, s24, 0x100000
	s_addc_u32 s25, s25, 0
	s_mov_b32 m0, s33
	v_lshl_add_u64 v[218:219], s[24:25], 0, v[194:195]
	ds_read_b128 v[158:161], v225 offset:32768
	ds_read_b128 v[170:173], v225 offset:33792
	ds_read_b128 v[174:177], v225 offset:34816
	ds_read_b128 v[178:181], v225 offset:35840
	ds_read_b128 v[182:185], v225 offset:36864
	ds_read_b128 v[186:189], v225 offset:37888
	ds_read_b128 v[200:203], v225 offset:38912
	ds_read_b128 v[204:207], v225 offset:39936
	global_load_lds_dwordx4 v[218:219], off
	v_lshl_add_u64 v[218:219], s[24:25], 0, v[190:191]
	s_mov_b32 m0, s49
	s_nop 0
	global_load_lds_dwordx4 v[218:219], off
	s_waitcnt vmcnt(8)
	s_waitcnt lgkmcnt(0)
	s_barrier
	v_mfma_f32_16x16x32_f16 v[166:169], v[66:69], v[158:161], v[166:169]
	v_mfma_f32_16x16x32_f16 v[162:165], v[78:81], v[158:161], v[162:165]
	v_mfma_f32_16x16x32_f16 v[146:149], v[66:69], v[174:177], v[146:149]
	v_mfma_f32_16x16x32_f16 v[142:145], v[78:81], v[174:177], v[142:145]
	v_mfma_f32_16x16x32_f16 v[130:133], v[66:69], v[182:185], v[130:133]
	v_mfma_f32_16x16x32_f16 v[126:129], v[78:81], v[182:185], v[126:129]
	v_mfma_f32_16x16x32_f16 v[114:117], v[66:69], v[200:203], v[114:117]
	v_mfma_f32_16x16x32_f16 v[110:113], v[78:81], v[200:203], v[110:113]
	v_mfma_f32_16x16x32_f16 v[166:169], v[70:73], v[170:173], v[166:169]
	v_mfma_f32_16x16x32_f16 v[162:165], v[82:85], v[170:173], v[162:165]
	v_mfma_f32_16x16x32_f16 v[146:149], v[70:73], v[178:181], v[146:149]
	v_mfma_f32_16x16x32_f16 v[142:145], v[82:85], v[178:181], v[142:145]
	v_mfma_f32_16x16x32_f16 v[130:133], v[70:73], v[186:189], v[130:133]
	v_mfma_f32_16x16x32_f16 v[126:129], v[82:85], v[186:189], v[126:129]
	v_mfma_f32_16x16x32_f16 v[114:117], v[70:73], v[204:207], v[114:117]
	v_mfma_f32_16x16x32_f16 v[110:113], v[82:85], v[204:207], v[110:113]
	v_mfma_f32_16x16x32_f16 v[154:157], v[86:89], v[158:161], v[154:157]
	v_mfma_f32_16x16x32_f16 v[150:153], v[94:97], v[158:161], v[150:153]
	v_mfma_f32_16x16x32_f16 v[138:141], v[86:89], v[174:177], v[138:141]
	v_mfma_f32_16x16x32_f16 v[134:137], v[94:97], v[174:177], v[134:137]
	v_mfma_f32_16x16x32_f16 v[122:125], v[86:89], v[182:185], v[122:125]
	v_mfma_f32_16x16x32_f16 v[118:121], v[94:97], v[182:185], v[118:121]
	v_mfma_f32_16x16x32_f16 v[106:109], v[86:89], v[200:203], v[106:109]
	v_mfma_f32_16x16x32_f16 v[102:105], v[94:97], v[200:203], v[102:105]
	v_mfma_f32_16x16x32_f16 v[154:157], v[90:93], v[170:173], v[154:157]
	v_mfma_f32_16x16x32_f16 v[150:153], v[98:101], v[170:173], v[150:153]
	v_mfma_f32_16x16x32_f16 v[138:141], v[90:93], v[178:181], v[138:141]
	v_mfma_f32_16x16x32_f16 v[134:137], v[98:101], v[178:181], v[134:137]
	v_mfma_f32_16x16x32_f16 v[122:125], v[90:93], v[186:189], v[122:125]
	v_mfma_f32_16x16x32_f16 v[118:121], v[98:101], v[186:189], v[118:121]
	v_mfma_f32_16x16x32_f16 v[106:109], v[90:93], v[204:207], v[106:109]
	v_mfma_f32_16x16x32_f16 v[102:105], v[98:101], v[204:207], v[102:105]
	s_barrier
; #define PG8_STAGE(bufoff, gbase, voff) do { _Pragma("unroll") for (int _i = 0; _i < 2; ++_i) \
;         __builtin_amdgcn_global_load_lds((const unsigned*)((const char*)(gbase) + (voff)[_i]), (PG8_LAS unsigned*)(lds + (bufoff) + ldsw + _i * 8192), 16, 0, 0); } while (0)
; #define PG8_LDA(dst, b, h) do { _Pragma("unroll") for (int m = 0; m < 4; ++m) _Pragma("unroll") for (int k = 0; k < 2; ++k) dst[m][k] = *(const PG8_LAS bf16x8*)(lds + PG8_SA(b, h) + aoff + m * 2048 + k * 1024); } while (0)
; #define PG8_MMA(ai, bj, At, Bt) do { __builtin_amdgcn_s_setprio(1); _Pragma("unroll") for (int m = 0; m < 4; ++m) _Pragma("unroll") for (int n = 0; n < 2; ++n) _Pragma("unroll") for (int k = 0; k < 2; ++k) \
;         acc[ai][bj][m][n] = __builtin_amdgcn_mfma_f32_16x16x32_f16(Bt[n][k], At[m][k], acc[ai][bj][m][n], 0, 0, 0); __builtin_amdgcn_s_setprio(0); } while (0)
; #define PG8_WAIT_V(n) asm volatile("s_waitcnt vmcnt(" #n ")" ::: "memory")
; #define PG8_WAIT_L(n) asm volatile("s_waitcnt lgkmcnt(" #n ")" ::: "memory")
; #define PG8_BAR __builtin_amdgcn_s_barrier()
; #define PG8_SCHED __builtin_amdgcn_sched_barrier(0)
; template <class Epi, class Sched, bool ALIGN_EPI = false, bool SP2 = false>
; __device__ __forceinline__ void gemm_phase(PG8_LAS unsigned char* lds, const Gemm g, const Sched& S, const Epi& E) {
;     ...
;             PG8_LDA(At, 1, 1); PG8_STAGE(PG8_SB(1, 0), b3, voffB); PG8_STAGE(PG8_SB(1, 1), b3 + hstep, voffB); PG8_STAGE(PG8_SA(1, 0), a3, voffA);
;             PG8_WAIT_V(8); PG8_WAIT_L(0); PG8_BAR; PG8_MMA(1, 0, At, B0); PG8_MMA(1, 1, At, B1); PG8_BAR; PG8_SCHED;
	s_add_i32 s13, s13, s5
	v_lshl_add_u64 v[208:209], v[208:209], 0, s[34:35]
	s_mov_b32 m0, s13
	ds_read_b128 v[158:161], v225 offset:49152
	ds_read_b128 v[170:173], v225 offset:50176
	ds_read_b128 v[174:177], v225 offset:51200
	ds_read_b128 v[178:181], v225 offset:52224
	ds_read_b128 v[182:185], v225 offset:53248
	ds_read_b128 v[186:189], v225 offset:54272
	ds_read_b128 v[200:203], v225 offset:55296
	ds_read_b128 v[204:207], v225 offset:56320
	global_load_lds_dwordx4 v[208:209], off
	s_add_i32 m0, s13, 0x2000
	s_add_u32 s22, s22, 0x100080
	v_lshl_add_u64 v[208:209], v[210:211], 0, s[34:35]
	s_addc_u32 s23, s23, 0
	s_add_i32 s13, s92, s5
	global_load_lds_dwordx4 v[208:209], off
	v_lshl_add_u64 v[208:209], s[22:23], 0, v[192:193]
	s_mov_b32 m0, s13
	s_nop 0
	global_load_lds_dwordx4 v[208:209], off
	v_lshl_add_u64 v[208:209], s[22:23], 0, v[14:15]
	s_add_i32 m0, s13, 0x2000
	s_nop 0
	global_load_lds_dwordx4 v[208:209], off
	v_lshl_add_u64 v[208:209], v[212:213], 0, s[34:35]
	s_mov_b32 m0, s72
	s_nop 0
	global_load_lds_dwordx4 v[208:209], off
	v_lshl_add_u64 v[208:209], v[214:215], 0, s[34:35]
	s_mov_b32 m0, s73
	s_nop 0
	global_load_lds_dwordx4 v[208:209], off
	s_waitcnt vmcnt(8)
	s_waitcnt lgkmcnt(0)
	s_barrier
	v_mfma_f32_16x16x32_f16 v[74:77], v[66:69], v[158:161], v[74:77]
	v_mfma_f32_16x16x32_f16 v[62:65], v[78:81], v[158:161], v[62:65]
	v_mfma_f32_16x16x32_f16 v[50:53], v[66:69], v[174:177], v[50:53]
	v_mfma_f32_16x16x32_f16 v[46:49], v[78:81], v[174:177], v[46:49]
	v_mfma_f32_16x16x32_f16 v[34:37], v[66:69], v[182:185], v[34:37]
	v_mfma_f32_16x16x32_f16 v[30:33], v[78:81], v[182:185], v[30:33]
	v_mfma_f32_16x16x32_f16 v[18:21], v[66:69], v[200:203], v[18:21]
	v_mfma_f32_16x16x32_f16 v[10:13], v[78:81], v[200:203], v[10:13]
	v_mfma_f32_16x16x32_f16 v[74:77], v[70:73], v[170:173], v[74:77]
	v_mfma_f32_16x16x32_f16 v[62:65], v[82:85], v[170:173], v[62:65]
	v_mfma_f32_16x16x32_f16 v[50:53], v[70:73], v[178:181], v[50:53]
	v_mfma_f32_16x16x32_f16 v[46:49], v[82:85], v[178:181], v[46:49]
	v_mfma_f32_16x16x32_f16 v[34:37], v[70:73], v[186:189], v[34:37]
	v_mfma_f32_16x16x32_f16 v[30:33], v[82:85], v[186:189], v[30:33]
	v_mfma_f32_16x16x32_f16 v[18:21], v[70:73], v[204:207], v[18:21]
	v_mfma_f32_16x16x32_f16 v[10:13], v[82:85], v[204:207], v[10:13]
	v_mfma_f32_16x16x32_f16 v[58:61], v[86:89], v[158:161], v[58:61]
	v_mfma_f32_16x16x32_f16 v[54:57], v[94:97], v[158:161], v[54:57]
	v_mfma_f32_16x16x32_f16 v[42:45], v[86:89], v[174:177], v[42:45]
	v_mfma_f32_16x16x32_f16 v[38:41], v[94:97], v[174:177], v[38:41]
	v_mfma_f32_16x16x32_f16 v[26:29], v[86:89], v[182:185], v[26:29]
	v_mfma_f32_16x16x32_f16 v[22:25], v[94:97], v[182:185], v[22:25]
	v_mfma_f32_16x16x32_f16 v[6:9], v[86:89], v[200:203], v[6:9]
	v_mfma_f32_16x16x32_f16 v[2:5], v[94:97], v[200:203], v[2:5]
	v_mfma_f32_16x16x32_f16 v[58:61], v[90:93], v[170:173], v[58:61]
	v_mfma_f32_16x16x32_f16 v[54:57], v[98:101], v[170:173], v[54:57]
	v_mfma_f32_16x16x32_f16 v[42:45], v[90:93], v[178:181], v[42:45]
	v_mfma_f32_16x16x32_f16 v[38:41], v[98:101], v[178:181], v[38:41]
	v_mfma_f32_16x16x32_f16 v[26:29], v[90:93], v[186:189], v[26:29]
	v_mfma_f32_16x16x32_f16 v[22:25], v[98:101], v[186:189], v[22:25]
	v_mfma_f32_16x16x32_f16 v[6:9], v[90:93], v[204:207], v[6:9]
	v_mfma_f32_16x16x32_f16 v[2:5], v[98:101], v[204:207], v[2:5]
	s_barrier
	s_add_i32 s12, s12, 2
	s_add_u32 vcc_lo, vcc_lo, 0x100
	s_addc_u32 vcc_hi, vcc_hi, 0
	s_add_u32 s76, s76, 0x100
	s_addc_u32 s77, s77, 0
	s_cmp_gt_u32 s12, 61
	s_cbranch_scc0 .LBB0_1134
	s_and_b64 vcc, exec, s[40:41]
	s_cbranch_vccz .LBB0_1137
	s_barrier
